# stack1c + MFMAs on structurally-zero weight column halves skipped (in_odd f_logit tile, in_even ckv/k_rope tiles)
# baseline (speedup 1.0000x reference)
; template <class Epi, class Sched, bool ALIGN_EPI = false, bool SP2 = false>
; __device__ __forceinline__ void gemm_phase(PG8_LAS unsigned char* lds, const Gemm g, const Sched& S, const Epi& E) {
;     ...
;         for (int t = 0; t < nt; t += 2) {
;             const bool last = (t == nt - 2);
;             const char* a1 = cA + (size_t)(t + 1) * kstep;
;             const char* a2 = last ? nA : cA + (size_t)(t + 2) * kstep; const char* b2 = last ? nB : cB + (size_t)(t + 2) * kstep;
;     ...
; #pragma unroll
;         for (int a = 0; a < 2; ++a)
; #pragma unroll
;             for (int b = 0; b < 2; ++b)
; #pragma unroll
;                 for (int m = 0; m < 4; ++m)
; #pragma unroll
;                     for (int n = 0; n < 2; ++n) acc[a][b][m][n] = (f32x4){0.f, 0.f, 0.f, 0.f};
;         cur = nxt; cA = nA; cB = nB; ++ui;
.LBB0_302:
	v_mov_b32_e32 v127, 0
	s_and_b64 vcc, exec, s[6:7]
	v_mov_b32_e32 v126, v127
	v_mov_b32_e32 v125, v127
	v_mov_b32_e32 v124, v127
	v_mov_b32_e32 v119, v127
	v_mov_b32_e32 v118, v127
	v_mov_b32_e32 v117, v127
	v_mov_b32_e32 v116, v127
	v_mov_b32_e32 v111, v127
	v_mov_b32_e32 v110, v127
	v_mov_b32_e32 v109, v127
	v_mov_b32_e32 v108, v127
	v_mov_b32_e32 v103, v127
	v_mov_b32_e32 v102, v127
	v_mov_b32_e32 v101, v127
	v_mov_b32_e32 v100, v127
	v_mov_b32_e32 v95, v127
	v_mov_b32_e32 v94, v127
	v_mov_b32_e32 v93, v127
	v_mov_b32_e32 v92, v127
	v_mov_b32_e32 v87, v127
	v_mov_b32_e32 v86, v127
	v_mov_b32_e32 v85, v127
	v_mov_b32_e32 v84, v127
	v_mov_b32_e32 v79, v127
	v_mov_b32_e32 v78, v127
	v_mov_b32_e32 v77, v127
	v_mov_b32_e32 v76, v127
	v_mov_b32_e32 v71, v127
	v_mov_b32_e32 v70, v127
	v_mov_b32_e32 v69, v127
	v_mov_b32_e32 v68, v127
	v_mov_b32_e32 v123, v127
	v_mov_b32_e32 v122, v127
	v_mov_b32_e32 v121, v127
	v_mov_b32_e32 v120, v127
	v_mov_b32_e32 v115, v127
	v_mov_b32_e32 v114, v127
	v_mov_b32_e32 v113, v127
	v_mov_b32_e32 v112, v127
	v_mov_b32_e32 v107, v127
	v_mov_b32_e32 v106, v127
	v_mov_b32_e32 v105, v127
	v_mov_b32_e32 v104, v127
	v_mov_b32_e32 v99, v127
	v_mov_b32_e32 v98, v127
	v_mov_b32_e32 v97, v127
	v_mov_b32_e32 v96, v127
	v_mov_b32_e32 v91, v127
	v_mov_b32_e32 v90, v127
	v_mov_b32_e32 v89, v127
	v_mov_b32_e32 v88, v127
	v_mov_b32_e32 v83, v127
	v_mov_b32_e32 v82, v127
	v_mov_b32_e32 v81, v127
	v_mov_b32_e32 v80, v127
	v_mov_b32_e32 v75, v127
	v_mov_b32_e32 v74, v127
	v_mov_b32_e32 v73, v127
	v_mov_b32_e32 v72, v127
	v_mov_b32_e32 v67, v127
	v_mov_b32_e32 v66, v127
	v_mov_b32_e32 v65, v127
	v_mov_b32_e32 v64, v127
	v_mov_b32_e32 v63, v127
	v_mov_b32_e32 v62, v127
	v_mov_b32_e32 v61, v127
	v_mov_b32_e32 v60, v127
	v_mov_b32_e32 v55, v127
	v_mov_b32_e32 v54, v127
	v_mov_b32_e32 v53, v127
	v_mov_b32_e32 v52, v127
	v_mov_b32_e32 v47, v127
	v_mov_b32_e32 v46, v127
	v_mov_b32_e32 v45, v127
	v_mov_b32_e32 v44, v127
	v_mov_b32_e32 v39, v127
	v_mov_b32_e32 v38, v127
	v_mov_b32_e32 v37, v127
	v_mov_b32_e32 v36, v127
	v_mov_b32_e32 v31, v127
	v_mov_b32_e32 v30, v127
	v_mov_b32_e32 v29, v127
	v_mov_b32_e32 v28, v127
	v_mov_b32_e32 v23, v127
	v_mov_b32_e32 v22, v127
	v_mov_b32_e32 v21, v127
	v_mov_b32_e32 v20, v127
	v_mov_b32_e32 v15, v127
	v_mov_b32_e32 v14, v127
	v_mov_b32_e32 v13, v127
	v_mov_b32_e32 v12, v127
	v_mov_b32_e32 v7, v127
	v_mov_b32_e32 v6, v127
	v_mov_b32_e32 v5, v127
	v_mov_b32_e32 v4, v127
	v_mov_b32_e32 v59, v127
	v_mov_b32_e32 v58, v127
	v_mov_b32_e32 v57, v127
	v_mov_b32_e32 v56, v127
	v_mov_b32_e32 v51, v127
	v_mov_b32_e32 v50, v127
	v_mov_b32_e32 v49, v127
	v_mov_b32_e32 v48, v127
	v_mov_b32_e32 v43, v127
	v_mov_b32_e32 v42, v127
	v_mov_b32_e32 v41, v127
	v_mov_b32_e32 v40, v127
	v_mov_b32_e32 v35, v127
	v_mov_b32_e32 v34, v127
	v_mov_b32_e32 v33, v127
	v_mov_b32_e32 v32, v127
	v_mov_b32_e32 v27, v127
	v_mov_b32_e32 v26, v127
	v_mov_b32_e32 v25, v127
	v_mov_b32_e32 v24, v127
	v_mov_b32_e32 v19, v127
	v_mov_b32_e32 v18, v127
	v_mov_b32_e32 v17, v127
	v_mov_b32_e32 v16, v127
	v_mov_b32_e32 v11, v127
	v_mov_b32_e32 v10, v127
	v_mov_b32_e32 v9, v127
	v_mov_b32_e32 v8, v127
	v_mov_b32_e32 v3, v127
	v_mov_b32_e32 v2, v127
	v_mov_b32_e32 v1, v127
	v_mov_b32_e32 v0, v127
	s_cbranch_vccnz .LBB0_305
	v_mov_b32_e32 v0, 0
	v_lshl_add_u64 v[158:159], v[158:159], 0, s[26:27]
	v_lshl_add_u64 v[160:161], v[160:161], 0, s[22:23]
	s_mov_b32 s10, 0
	v_mov_b32_e32 v1, v0
	v_mov_b32_e32 v2, v0
	v_mov_b32_e32 v3, v0
	v_mov_b32_e32 v8, v0
	v_mov_b32_e32 v9, v0
	v_mov_b32_e32 v10, v0
	v_mov_b32_e32 v11, v0
	v_mov_b32_e32 v16, v0
	v_mov_b32_e32 v17, v0
	v_mov_b32_e32 v18, v0
	v_mov_b32_e32 v19, v0
	v_mov_b32_e32 v24, v0
	v_mov_b32_e32 v25, v0
	v_mov_b32_e32 v26, v0
	v_mov_b32_e32 v27, v0
	v_mov_b32_e32 v32, v0
	v_mov_b32_e32 v33, v0
	v_mov_b32_e32 v34, v0
	v_mov_b32_e32 v35, v0
	v_mov_b32_e32 v40, v0
	v_mov_b32_e32 v41, v0
	v_mov_b32_e32 v42, v0
	v_mov_b32_e32 v43, v0
	v_mov_b32_e32 v48, v0
	v_mov_b32_e32 v49, v0
	v_mov_b32_e32 v50, v0
	v_mov_b32_e32 v51, v0
	v_mov_b32_e32 v56, v0
	v_mov_b32_e32 v57, v0
	v_mov_b32_e32 v58, v0
	v_mov_b32_e32 v59, v0
	v_mov_b32_e32 v4, v0
	v_mov_b32_e32 v5, v0
	v_mov_b32_e32 v6, v0
	v_mov_b32_e32 v7, v0
	v_mov_b32_e32 v12, v0
	v_mov_b32_e32 v13, v0
	v_mov_b32_e32 v14, v0
	v_mov_b32_e32 v15, v0
	v_mov_b32_e32 v20, v0
	v_mov_b32_e32 v21, v0
	v_mov_b32_e32 v22, v0
	v_mov_b32_e32 v23, v0
	v_mov_b32_e32 v28, v0
	v_mov_b32_e32 v29, v0
	v_mov_b32_e32 v30, v0
	v_mov_b32_e32 v31, v0
	v_mov_b32_e32 v36, v0
	v_mov_b32_e32 v37, v0
	v_mov_b32_e32 v38, v0
	v_mov_b32_e32 v39, v0
	v_mov_b32_e32 v44, v0
	v_mov_b32_e32 v45, v0
	v_mov_b32_e32 v46, v0
	v_mov_b32_e32 v47, v0
	v_mov_b32_e32 v52, v0
	v_mov_b32_e32 v53, v0
	v_mov_b32_e32 v54, v0
	v_mov_b32_e32 v55, v0
	v_mov_b32_e32 v60, v0
	v_mov_b32_e32 v61, v0
	v_mov_b32_e32 v62, v0
	v_mov_b32_e32 v63, v0
	v_mov_b32_e32 v64, v0
	v_mov_b32_e32 v65, v0
	v_mov_b32_e32 v66, v0
	v_mov_b32_e32 v67, v0
	v_mov_b32_e32 v72, v0
	v_mov_b32_e32 v73, v0
	v_mov_b32_e32 v74, v0
	v_mov_b32_e32 v75, v0
	v_mov_b32_e32 v80, v0
	v_mov_b32_e32 v81, v0
	v_mov_b32_e32 v82, v0
	v_mov_b32_e32 v83, v0
	v_mov_b32_e32 v88, v0
	v_mov_b32_e32 v89, v0
	v_mov_b32_e32 v90, v0
	v_mov_b32_e32 v91, v0
	v_mov_b32_e32 v96, v0
	v_mov_b32_e32 v97, v0
	v_mov_b32_e32 v98, v0
	v_mov_b32_e32 v99, v0
	v_mov_b32_e32 v104, v0
	v_mov_b32_e32 v105, v0
	v_mov_b32_e32 v106, v0
	v_mov_b32_e32 v107, v0
	v_mov_b32_e32 v112, v0
	v_mov_b32_e32 v113, v0
	v_mov_b32_e32 v114, v0
	v_mov_b32_e32 v115, v0
	v_mov_b32_e32 v120, v0
	v_mov_b32_e32 v121, v0
	v_mov_b32_e32 v122, v0
	v_mov_b32_e32 v123, v0
	v_mov_b32_e32 v68, v0
	v_mov_b32_e32 v69, v0
	v_mov_b32_e32 v70, v0
	v_mov_b32_e32 v71, v0
	v_mov_b32_e32 v76, v0
	v_mov_b32_e32 v77, v0
	v_mov_b32_e32 v78, v0
	v_mov_b32_e32 v79, v0
	v_mov_b32_e32 v84, v0
	v_mov_b32_e32 v85, v0
	v_mov_b32_e32 v86, v0
	v_mov_b32_e32 v87, v0
	v_mov_b32_e32 v92, v0
	v_mov_b32_e32 v93, v0
	v_mov_b32_e32 v94, v0
	v_mov_b32_e32 v95, v0
	v_mov_b32_e32 v100, v0
	v_mov_b32_e32 v101, v0
	v_mov_b32_e32 v102, v0
	v_mov_b32_e32 v103, v0
	v_mov_b32_e32 v108, v0
	v_mov_b32_e32 v109, v0
	v_mov_b32_e32 v110, v0
	v_mov_b32_e32 v111, v0
	v_mov_b32_e32 v116, v0
	v_mov_b32_e32 v117, v0
	v_mov_b32_e32 v118, v0
	v_mov_b32_e32 v119, v0
	v_mov_b32_e32 v124, v0
	v_mov_b32_e32 v125, v0
	v_mov_b32_e32 v126, v0
	v_mov_b32_e32 v127, v0
	.p2align	6

; template <class Epi, class Sched, bool ALIGN_EPI = false, bool SP2 = false>
; __device__ __forceinline__ void gemm_phase(PG8_LAS unsigned char* lds, const Gemm g, const Sched& S, const Epi& E) {
;     ...
;         for (int t = 0; t < nt; t += 2) {
;             const bool last = (t == nt - 2);
;             const char* a1 = cA + (size_t)(t + 1) * kstep;
;             const char* a2 = last ? nA : cA + (size_t)(t + 2) * kstep; const char* b2 = last ? nB : cB + (size_t)(t + 2) * kstep;
;     ...
; #pragma unroll
;         for (int a = 0; a < 2; ++a)
; #pragma unroll
;             for (int b = 0; b < 2; ++b)
; #pragma unroll
;                 for (int m = 0; m < 4; ++m)
; #pragma unroll
;                     for (int n = 0; n < 2; ++n) acc[a][b][m][n] = (f32x4){0.f, 0.f, 0.f, 0.f};
;         cur = nxt; cA = nA; cB = nB; ++ui;
.LBB0_369:
	v_mov_b32_e32 v127, 0
	s_and_b64 vcc, exec, s[8:9]
	v_mov_b32_e32 v126, v127
	v_mov_b32_e32 v125, v127
	v_mov_b32_e32 v124, v127
	v_mov_b32_e32 v131, v127
	v_mov_b32_e32 v130, v127
	v_mov_b32_e32 v129, v127
	v_mov_b32_e32 v128, v127
	v_mov_b32_e32 v115, v127
	v_mov_b32_e32 v114, v127
	v_mov_b32_e32 v113, v127
	v_mov_b32_e32 v112, v127
	v_mov_b32_e32 v111, v127
	v_mov_b32_e32 v110, v127
	v_mov_b32_e32 v109, v127
	v_mov_b32_e32 v108, v127
	v_mov_b32_e32 v99, v127
	v_mov_b32_e32 v98, v127
	v_mov_b32_e32 v97, v127
	v_mov_b32_e32 v96, v127
	v_mov_b32_e32 v95, v127
	v_mov_b32_e32 v94, v127
	v_mov_b32_e32 v93, v127
	v_mov_b32_e32 v92, v127
	v_mov_b32_e32 v83, v127
	v_mov_b32_e32 v82, v127
	v_mov_b32_e32 v81, v127
	v_mov_b32_e32 v80, v127
	v_mov_b32_e32 v79, v127
	v_mov_b32_e32 v78, v127
	v_mov_b32_e32 v77, v127
	v_mov_b32_e32 v76, v127
	v_mov_b32_e32 v123, v127
	v_mov_b32_e32 v122, v127
	v_mov_b32_e32 v121, v127
	v_mov_b32_e32 v120, v127
	v_mov_b32_e32 v119, v127
	v_mov_b32_e32 v118, v127
	v_mov_b32_e32 v117, v127
	v_mov_b32_e32 v116, v127
	v_mov_b32_e32 v107, v127
	v_mov_b32_e32 v106, v127
	v_mov_b32_e32 v105, v127
	v_mov_b32_e32 v104, v127
	v_mov_b32_e32 v103, v127
	v_mov_b32_e32 v102, v127
	v_mov_b32_e32 v101, v127
	v_mov_b32_e32 v100, v127
	v_mov_b32_e32 v91, v127
	v_mov_b32_e32 v90, v127
	v_mov_b32_e32 v89, v127
	v_mov_b32_e32 v88, v127
	v_mov_b32_e32 v87, v127
	v_mov_b32_e32 v86, v127
	v_mov_b32_e32 v85, v127
	v_mov_b32_e32 v84, v127
	v_mov_b32_e32 v75, v127
	v_mov_b32_e32 v74, v127
	v_mov_b32_e32 v73, v127
	v_mov_b32_e32 v72, v127
	v_mov_b32_e32 v71, v127
	v_mov_b32_e32 v70, v127
	v_mov_b32_e32 v69, v127
	v_mov_b32_e32 v68, v127
	v_mov_b32_e32 v67, v127
	v_mov_b32_e32 v66, v127
	v_mov_b32_e32 v65, v127
	v_mov_b32_e32 v64, v127
	v_mov_b32_e32 v63, v127
	v_mov_b32_e32 v62, v127
	v_mov_b32_e32 v61, v127
	v_mov_b32_e32 v60, v127
	v_mov_b32_e32 v51, v127
	v_mov_b32_e32 v50, v127
	v_mov_b32_e32 v49, v127
	v_mov_b32_e32 v48, v127
	v_mov_b32_e32 v47, v127
	v_mov_b32_e32 v46, v127
	v_mov_b32_e32 v45, v127
	v_mov_b32_e32 v44, v127
	v_mov_b32_e32 v35, v127
	v_mov_b32_e32 v34, v127
	v_mov_b32_e32 v33, v127
	v_mov_b32_e32 v32, v127
	v_mov_b32_e32 v31, v127
	v_mov_b32_e32 v30, v127
	v_mov_b32_e32 v29, v127
	v_mov_b32_e32 v28, v127
	v_mov_b32_e32 v19, v127
	v_mov_b32_e32 v18, v127
	v_mov_b32_e32 v17, v127
	v_mov_b32_e32 v16, v127
	v_mov_b32_e32 v15, v127
	v_mov_b32_e32 v14, v127
	v_mov_b32_e32 v13, v127
	v_mov_b32_e32 v12, v127
	v_mov_b32_e32 v59, v127
	v_mov_b32_e32 v58, v127
	v_mov_b32_e32 v57, v127
	v_mov_b32_e32 v56, v127
	v_mov_b32_e32 v55, v127
	v_mov_b32_e32 v54, v127
	v_mov_b32_e32 v53, v127
	v_mov_b32_e32 v52, v127
	v_mov_b32_e32 v43, v127
	v_mov_b32_e32 v42, v127
	v_mov_b32_e32 v41, v127
	v_mov_b32_e32 v40, v127
	v_mov_b32_e32 v39, v127
	v_mov_b32_e32 v38, v127
	v_mov_b32_e32 v37, v127
	v_mov_b32_e32 v36, v127
	v_mov_b32_e32 v27, v127
	v_mov_b32_e32 v26, v127
	v_mov_b32_e32 v25, v127
	v_mov_b32_e32 v24, v127
	v_mov_b32_e32 v23, v127
	v_mov_b32_e32 v22, v127
	v_mov_b32_e32 v21, v127
	v_mov_b32_e32 v20, v127
	v_mov_b32_e32 v11, v127
	v_mov_b32_e32 v10, v127
	v_mov_b32_e32 v9, v127
	v_mov_b32_e32 v8, v127
	v_mov_b32_e32 v7, v127
	v_mov_b32_e32 v6, v127
	s_waitcnt lgkmcnt(0)
	v_mov_b32_e32 v5, v127
	v_mov_b32_e32 v4, v127
	s_cbranch_vccnz .LBB0_372
	v_mov_b32_e32 v4, 0
	v_lshl_add_u64 v[132:133], v[132:133], 0, s[26:27]
	v_lshl_add_u64 v[134:135], v[134:135], 0, s[22:23]
	s_mov_b32 s12, 0
	v_mov_b32_e32 v5, v4
	v_mov_b32_e32 v6, v4
	v_mov_b32_e32 v7, v4
	v_mov_b32_e32 v8, v4
	v_mov_b32_e32 v9, v4
	v_mov_b32_e32 v10, v4
	v_mov_b32_e32 v11, v4
	v_mov_b32_e32 v20, v4
	v_mov_b32_e32 v21, v4
	v_mov_b32_e32 v22, v4
	v_mov_b32_e32 v23, v4
	v_mov_b32_e32 v24, v4
	v_mov_b32_e32 v25, v4
	v_mov_b32_e32 v26, v4
	v_mov_b32_e32 v27, v4
	v_mov_b32_e32 v36, v4
	v_mov_b32_e32 v37, v4
	v_mov_b32_e32 v38, v4
	v_mov_b32_e32 v39, v4
	v_mov_b32_e32 v40, v4
	v_mov_b32_e32 v41, v4
	v_mov_b32_e32 v42, v4
	v_mov_b32_e32 v43, v4
	v_mov_b32_e32 v52, v4
	v_mov_b32_e32 v53, v4
	v_mov_b32_e32 v54, v4
	v_mov_b32_e32 v55, v4
	v_mov_b32_e32 v56, v4
	v_mov_b32_e32 v57, v4
	v_mov_b32_e32 v58, v4
	v_mov_b32_e32 v59, v4
	v_mov_b32_e32 v12, v4
	v_mov_b32_e32 v13, v4
	v_mov_b32_e32 v14, v4
	v_mov_b32_e32 v15, v4
	v_mov_b32_e32 v16, v4
	v_mov_b32_e32 v17, v4
	v_mov_b32_e32 v18, v4
	v_mov_b32_e32 v19, v4
	v_mov_b32_e32 v28, v4
	v_mov_b32_e32 v29, v4
	v_mov_b32_e32 v30, v4
	v_mov_b32_e32 v31, v4
	v_mov_b32_e32 v32, v4
	v_mov_b32_e32 v33, v4
	v_mov_b32_e32 v34, v4
	v_mov_b32_e32 v35, v4
	v_mov_b32_e32 v44, v4
	v_mov_b32_e32 v45, v4
	v_mov_b32_e32 v46, v4
	v_mov_b32_e32 v47, v4
	v_mov_b32_e32 v48, v4
	v_mov_b32_e32 v49, v4
	v_mov_b32_e32 v50, v4
	v_mov_b32_e32 v51, v4
	v_mov_b32_e32 v60, v4
	v_mov_b32_e32 v61, v4
	v_mov_b32_e32 v62, v4
	v_mov_b32_e32 v63, v4
	v_mov_b32_e32 v64, v4
	v_mov_b32_e32 v65, v4
	v_mov_b32_e32 v66, v4
	v_mov_b32_e32 v67, v4
	v_mov_b32_e32 v68, v4
	v_mov_b32_e32 v69, v4
	v_mov_b32_e32 v70, v4
	v_mov_b32_e32 v71, v4
	v_mov_b32_e32 v72, v4
	v_mov_b32_e32 v73, v4
	v_mov_b32_e32 v74, v4
	v_mov_b32_e32 v75, v4
	v_mov_b32_e32 v84, v4
	v_mov_b32_e32 v85, v4
	v_mov_b32_e32 v86, v4
	v_mov_b32_e32 v87, v4
	v_mov_b32_e32 v88, v4
	v_mov_b32_e32 v89, v4
	v_mov_b32_e32 v90, v4
	v_mov_b32_e32 v91, v4
	v_mov_b32_e32 v100, v4
	v_mov_b32_e32 v101, v4
	v_mov_b32_e32 v102, v4
	v_mov_b32_e32 v103, v4
	v_mov_b32_e32 v104, v4
	v_mov_b32_e32 v105, v4
	v_mov_b32_e32 v106, v4
	v_mov_b32_e32 v107, v4
	v_mov_b32_e32 v116, v4
	v_mov_b32_e32 v117, v4
	v_mov_b32_e32 v118, v4
	v_mov_b32_e32 v119, v4
	v_mov_b32_e32 v120, v4
	v_mov_b32_e32 v121, v4
	v_mov_b32_e32 v122, v4
	v_mov_b32_e32 v123, v4
	v_mov_b32_e32 v76, v4
	v_mov_b32_e32 v77, v4
	v_mov_b32_e32 v78, v4
	v_mov_b32_e32 v79, v4
	v_mov_b32_e32 v80, v4
	v_mov_b32_e32 v81, v4
	v_mov_b32_e32 v82, v4
	v_mov_b32_e32 v83, v4
	v_mov_b32_e32 v92, v4
	v_mov_b32_e32 v93, v4
	v_mov_b32_e32 v94, v4
	v_mov_b32_e32 v95, v4
	v_mov_b32_e32 v96, v4
	v_mov_b32_e32 v97, v4
	v_mov_b32_e32 v98, v4
	v_mov_b32_e32 v99, v4
	v_mov_b32_e32 v108, v4
	v_mov_b32_e32 v109, v4
	v_mov_b32_e32 v110, v4
	v_mov_b32_e32 v111, v4
	v_mov_b32_e32 v112, v4
	v_mov_b32_e32 v113, v4
	v_mov_b32_e32 v114, v4
	v_mov_b32_e32 v115, v4
	v_mov_b32_e32 v128, v4
	v_mov_b32_e32 v129, v4
	v_mov_b32_e32 v130, v4
	v_mov_b32_e32 v131, v4
	v_mov_b32_e32 v124, v4
	v_mov_b32_e32 v125, v4
	v_mov_b32_e32 v126, v4
	v_mov_b32_e32 v127, v4
	.p2align	6

; template <class Epi, class Sched, bool ALIGN_EPI = false, bool SP2 = false>
; __device__ __forceinline__ void gemm_phase(PG8_LAS unsigned char* lds, const Gemm g, const Sched& S, const Epi& E) {
;     ...
;         for (int t = 0; t < nt; t += 2) {
;             const bool last = (t == nt - 2);
;             const char* a1 = cA + (size_t)(t + 1) * kstep;
;             const char* a2 = last ? nA : cA + (size_t)(t + 2) * kstep; const char* b2 = last ? nB : cB + (size_t)(t + 2) * kstep;
;     ...
; #pragma unroll
;         for (int a = 0; a < 2; ++a)
; #pragma unroll
;             for (int b = 0; b < 2; ++b)
; #pragma unroll
;                 for (int m = 0; m < 4; ++m)
; #pragma unroll
;                     for (int n = 0; n < 2; ++n) acc[a][b][m][n] = (f32x4){0.f, 0.f, 0.f, 0.f};
;         cur = nxt; cA = nA; cB = nB; ++ui;
.LBB0_452:
	v_mov_b32_e32 v127, 0
	s_andn2_b64 vcc, exec, s[26:27]
	v_mov_b32_e32 v126, v127
	v_mov_b32_e32 v125, v127
	v_mov_b32_e32 v124, v127
	v_mov_b32_e32 v123, v127
	v_mov_b32_e32 v122, v127
	v_mov_b32_e32 v121, v127
	v_mov_b32_e32 v120, v127
	v_mov_b32_e32 v111, v127
	v_mov_b32_e32 v110, v127
	v_mov_b32_e32 v109, v127
	v_mov_b32_e32 v108, v127
	v_mov_b32_e32 v107, v127
	v_mov_b32_e32 v106, v127
	v_mov_b32_e32 v105, v127
	v_mov_b32_e32 v104, v127
	v_mov_b32_e32 v95, v127
	v_mov_b32_e32 v94, v127
	v_mov_b32_e32 v93, v127
	v_mov_b32_e32 v92, v127
	v_mov_b32_e32 v91, v127
	v_mov_b32_e32 v90, v127
	v_mov_b32_e32 v89, v127
	v_mov_b32_e32 v88, v127
	v_mov_b32_e32 v79, v127
	v_mov_b32_e32 v78, v127
	v_mov_b32_e32 v77, v127
	v_mov_b32_e32 v76, v127
	v_mov_b32_e32 v75, v127
	v_mov_b32_e32 v74, v127
	v_mov_b32_e32 v73, v127
	v_mov_b32_e32 v72, v127
	v_mov_b32_e32 v119, v127
	v_mov_b32_e32 v118, v127
	v_mov_b32_e32 v117, v127
	v_mov_b32_e32 v116, v127
	v_mov_b32_e32 v115, v127
	v_mov_b32_e32 v114, v127
	v_mov_b32_e32 v113, v127
	v_mov_b32_e32 v112, v127
	v_mov_b32_e32 v103, v127
	v_mov_b32_e32 v102, v127
	v_mov_b32_e32 v101, v127
	v_mov_b32_e32 v100, v127
	v_mov_b32_e32 v99, v127
	v_mov_b32_e32 v98, v127
	v_mov_b32_e32 v97, v127
	v_mov_b32_e32 v96, v127
	v_mov_b32_e32 v87, v127
	v_mov_b32_e32 v86, v127
	v_mov_b32_e32 v85, v127
	v_mov_b32_e32 v84, v127
	v_mov_b32_e32 v83, v127
	v_mov_b32_e32 v82, v127
	v_mov_b32_e32 v81, v127
	v_mov_b32_e32 v80, v127
	v_mov_b32_e32 v71, v127
	v_mov_b32_e32 v70, v127
	v_mov_b32_e32 v69, v127
	v_mov_b32_e32 v68, v127
	v_mov_b32_e32 v67, v127
	v_mov_b32_e32 v66, v127
	v_mov_b32_e32 v65, v127
	v_mov_b32_e32 v64, v127
	v_mov_b32_e32 v63, v127
	v_mov_b32_e32 v62, v127
	v_mov_b32_e32 v61, v127
	v_mov_b32_e32 v60, v127
	v_mov_b32_e32 v59, v127
	v_mov_b32_e32 v58, v127
	v_mov_b32_e32 v57, v127
	v_mov_b32_e32 v56, v127
	v_mov_b32_e32 v47, v127
	v_mov_b32_e32 v46, v127
	v_mov_b32_e32 v45, v127
	v_mov_b32_e32 v44, v127
	v_mov_b32_e32 v43, v127
	v_mov_b32_e32 v42, v127
	v_mov_b32_e32 v41, v127
	v_mov_b32_e32 v40, v127
	v_mov_b32_e32 v31, v127
	v_mov_b32_e32 v30, v127
	v_mov_b32_e32 v29, v127
	v_mov_b32_e32 v28, v127
	v_mov_b32_e32 v27, v127
	v_mov_b32_e32 v26, v127
	v_mov_b32_e32 v25, v127
	v_mov_b32_e32 v24, v127
	v_mov_b32_e32 v15, v127
	v_mov_b32_e32 v14, v127
	v_mov_b32_e32 v13, v127
	v_mov_b32_e32 v12, v127
	v_mov_b32_e32 v11, v127
	v_mov_b32_e32 v10, v127
	v_mov_b32_e32 v9, v127
	v_mov_b32_e32 v8, v127
	v_mov_b32_e32 v55, v127
	v_mov_b32_e32 v54, v127
	v_mov_b32_e32 v53, v127
	v_mov_b32_e32 v52, v127
	v_mov_b32_e32 v51, v127
	v_mov_b32_e32 v50, v127
	v_mov_b32_e32 v49, v127
	v_mov_b32_e32 v48, v127
	v_mov_b32_e32 v39, v127
	s_waitcnt lgkmcnt(0)
	v_mov_b32_e32 v38, v127
	v_mov_b32_e32 v37, v127
	v_mov_b32_e32 v36, v127
	v_mov_b32_e32 v35, v127
	v_mov_b32_e32 v34, v127
	v_mov_b32_e32 v33, v127
	v_mov_b32_e32 v32, v127
	v_mov_b32_e32 v23, v127
	v_mov_b32_e32 v22, v127
	v_mov_b32_e32 v21, v127
	v_mov_b32_e32 v20, v127
	v_mov_b32_e32 v19, v127
	v_mov_b32_e32 v18, v127
	v_mov_b32_e32 v17, v127
	v_mov_b32_e32 v16, v127
	v_mov_b32_e32 v7, v127
	v_mov_b32_e32 v6, v127
	v_mov_b32_e32 v5, v127
	v_mov_b32_e32 v4, v127
	v_mov_b32_e32 v3, v127
	v_mov_b32_e32 v2, v127
	v_mov_b32_e32 v1, v127
	v_mov_b32_e32 v0, v127
	s_cbranch_vccnz .LBB0_455
	v_mov_b32_e32 v0, 0
	v_lshl_add_u64 v[128:129], v[128:129], 0, s[34:35]
	v_lshl_add_u64 v[130:131], v[130:131], 0, s[24:25]
	s_mov_b32 s12, 0
	v_mov_b32_e32 v1, v0
	v_mov_b32_e32 v2, v0
	v_mov_b32_e32 v3, v0
	v_mov_b32_e32 v4, v0
	v_mov_b32_e32 v5, v0
	v_mov_b32_e32 v6, v0
	v_mov_b32_e32 v7, v0
	v_mov_b32_e32 v16, v0
	v_mov_b32_e32 v17, v0
	v_mov_b32_e32 v18, v0
	v_mov_b32_e32 v19, v0
	v_mov_b32_e32 v20, v0
	v_mov_b32_e32 v21, v0
	v_mov_b32_e32 v22, v0
	v_mov_b32_e32 v23, v0
	v_mov_b32_e32 v32, v0
	v_mov_b32_e32 v33, v0
	v_mov_b32_e32 v34, v0
	v_mov_b32_e32 v35, v0
	v_mov_b32_e32 v36, v0
	v_mov_b32_e32 v37, v0
	v_mov_b32_e32 v38, v0
	v_mov_b32_e32 v39, v0
	v_mov_b32_e32 v48, v0
	v_mov_b32_e32 v49, v0
	v_mov_b32_e32 v50, v0
	v_mov_b32_e32 v51, v0
	v_mov_b32_e32 v52, v0
	v_mov_b32_e32 v53, v0
	v_mov_b32_e32 v54, v0
	v_mov_b32_e32 v55, v0
	v_mov_b32_e32 v8, v0
	v_mov_b32_e32 v9, v0
	v_mov_b32_e32 v10, v0
	v_mov_b32_e32 v11, v0
	v_mov_b32_e32 v12, v0
	v_mov_b32_e32 v13, v0
	v_mov_b32_e32 v14, v0
	v_mov_b32_e32 v15, v0
	v_mov_b32_e32 v24, v0
	v_mov_b32_e32 v25, v0
	v_mov_b32_e32 v26, v0
	v_mov_b32_e32 v27, v0
	v_mov_b32_e32 v28, v0
	v_mov_b32_e32 v29, v0
	v_mov_b32_e32 v30, v0
	v_mov_b32_e32 v31, v0
	v_mov_b32_e32 v40, v0
	v_mov_b32_e32 v41, v0
	v_mov_b32_e32 v42, v0
	v_mov_b32_e32 v43, v0
	v_mov_b32_e32 v44, v0
	v_mov_b32_e32 v45, v0
	v_mov_b32_e32 v46, v0
	v_mov_b32_e32 v47, v0
	v_mov_b32_e32 v56, v0
	v_mov_b32_e32 v57, v0
	v_mov_b32_e32 v58, v0
	v_mov_b32_e32 v59, v0
	v_mov_b32_e32 v60, v0
	v_mov_b32_e32 v61, v0
	v_mov_b32_e32 v62, v0
	v_mov_b32_e32 v63, v0
	v_mov_b32_e32 v64, v0
	v_mov_b32_e32 v65, v0
	v_mov_b32_e32 v66, v0
	v_mov_b32_e32 v67, v0
	v_mov_b32_e32 v68, v0
	v_mov_b32_e32 v69, v0
	v_mov_b32_e32 v70, v0
	v_mov_b32_e32 v71, v0
	v_mov_b32_e32 v80, v0
	v_mov_b32_e32 v81, v0
	v_mov_b32_e32 v82, v0
	v_mov_b32_e32 v83, v0
	v_mov_b32_e32 v84, v0
	v_mov_b32_e32 v85, v0
	v_mov_b32_e32 v86, v0
	v_mov_b32_e32 v87, v0
	v_mov_b32_e32 v96, v0
	v_mov_b32_e32 v97, v0
	v_mov_b32_e32 v98, v0
	v_mov_b32_e32 v99, v0
	v_mov_b32_e32 v100, v0
	v_mov_b32_e32 v101, v0
	v_mov_b32_e32 v102, v0
	v_mov_b32_e32 v103, v0
	v_mov_b32_e32 v112, v0
	v_mov_b32_e32 v113, v0
	v_mov_b32_e32 v114, v0
	v_mov_b32_e32 v115, v0
	v_mov_b32_e32 v116, v0
	v_mov_b32_e32 v117, v0
	v_mov_b32_e32 v118, v0
	v_mov_b32_e32 v119, v0
	v_mov_b32_e32 v72, v0
	v_mov_b32_e32 v73, v0
	v_mov_b32_e32 v74, v0
	v_mov_b32_e32 v75, v0
	v_mov_b32_e32 v76, v0
	v_mov_b32_e32 v77, v0
	v_mov_b32_e32 v78, v0
	v_mov_b32_e32 v79, v0
	v_mov_b32_e32 v88, v0
	v_mov_b32_e32 v89, v0
	v_mov_b32_e32 v90, v0
	v_mov_b32_e32 v91, v0
	v_mov_b32_e32 v92, v0
	v_mov_b32_e32 v93, v0
	v_mov_b32_e32 v94, v0
	v_mov_b32_e32 v95, v0
	v_mov_b32_e32 v104, v0
	v_mov_b32_e32 v105, v0
	v_mov_b32_e32 v106, v0
	v_mov_b32_e32 v107, v0
	v_mov_b32_e32 v108, v0
	v_mov_b32_e32 v109, v0
	v_mov_b32_e32 v110, v0
	v_mov_b32_e32 v111, v0
	v_mov_b32_e32 v120, v0
	v_mov_b32_e32 v121, v0
	v_mov_b32_e32 v122, v0
	v_mov_b32_e32 v123, v0
	v_mov_b32_e32 v124, v0
	v_mov_b32_e32 v125, v0
	v_mov_b32_e32 v126, v0
	v_mov_b32_e32 v127, v0
	.p2align	6
; #define PG8_STAGE(bufoff, gbase, voff) do { _Pragma("unroll") for (int _i = 0; _i < 2; ++_i) \
;         __builtin_amdgcn_global_load_lds((const unsigned*)((const char*)(gbase) + (voff)[_i]), (PG8_LAS unsigned*)(lds + (bufoff) + ldsw + _i * 8192), 16, 0, 0); } while (0)
; #define PG8_LDA(dst, b, h) do { _Pragma("unroll") for (int m = 0; m < 4; ++m) _Pragma("unroll") for (int k = 0; k < 2; ++k) dst[m][k] = *(const PG8_LAS bf16x8*)(lds + PG8_SA(b, h) + aoff + m * 2048 + k * 1024); } while (0)
; #define PG8_LDB(dst, b, h) do { _Pragma("unroll") for (int n = 0; n < 2; ++n) _Pragma("unroll") for (int k = 0; k < 2; ++k) dst[n][k] = *(const PG8_LAS bf16x8*)(lds + PG8_SB(b, h) + boff + n * 2048 + k * 1024); } while (0)
; #define PG8_MMA(ai, bj, At, Bt) do { __builtin_amdgcn_s_setprio(1); _Pragma("unroll") for (int m = 0; m < 4; ++m) _Pragma("unroll") for (int n = 0; n < 2; ++n) _Pragma("unroll") for (int k = 0; k < 2; ++k) \
;         acc[ai][bj][m][n] = __builtin_amdgcn_mfma_f32_16x16x32_bf16(Bt[n][k], At[m][k], acc[ai][bj][m][n], 0, 0, 0); __builtin_amdgcn_s_setprio(0); } while (0)
; #define PG8_WAIT_V(n) asm volatile("s_waitcnt vmcnt(" #n ")" ::: "memory")
; #define PG8_WAIT_L(n) asm volatile("s_waitcnt lgkmcnt(" #n ")" ::: "memory")
; template <class Epi, class Sched, bool ALIGN_EPI = false, bool SP2 = false>
; __device__ __forceinline__ void gemm_phase(PG8_LAS unsigned char* lds, const Gemm g, const Sched& S, const Epi& E) {
;     ...
;             const bool last = (t == nt - 2);
;             const char* a1 = cA + (size_t)(t + 1) * kstep;
;             const char* a2 = last ? nA : cA + (size_t)(t + 2) * kstep; const char* b2 = last ? nB : cB + (size_t)(t + 2) * kstep;
;             const char* a3 = a2 + kstep; const char* b3 = b2 + kstep;
;             if (last && has_next) S.a_ready(nxt);
;             if constexpr (SP2) {
;             PG8_LDB(B0, 0, 0); PG8_LDB(B1, 0, 1); PG8_SCHED; PG8_LDA(At, 0, 0); PG8_STAGE(PG8_SA(1, 1), a1 + hstep, voffA);
;             PG8_WAIT_V(8); PG8_WAIT_L(0); PG8_BAR; PG8_MMA(0, 0, At, B0); PG8_MMA(0, 1, At, B1); PG8_BAR; PG8_SCHED;
;             PG8_LDA(At, 0, 1); PG8_STAGE(PG8_SB(0, 0), b2, voffB); PG8_STAGE(PG8_SB(0, 1), b2 + hstep, voffB); PG8_STAGE(PG8_SA(0, 0), a2, voffA);
;             PG8_WAIT_V(8); PG8_WAIT_L(0); PG8_BAR; PG8_MMA(1, 0, At, B0); PG8_MMA(1, 1, At, B1); PG8_BAR; PG8_SCHED;
.LBB0_454:
	v_add_u32_e32 v165, s69, v171
	v_add_u32_e32 v167, s70, v171
	ds_read_b128 v[132:135], v165
	ds_read_b128 v[136:139], v165 offset:1024
	ds_read_b128 v[176:179], v165 offset:2048
	ds_read_b128 v[180:183], v165 offset:3072
	ds_read_b128 v[184:187], v167
	ds_read_b128 v[188:191], v167 offset:1024
	ds_read_b128 v[192:195], v167 offset:2048
	ds_read_b128 v[196:199], v167 offset:3072
	s_cmp_eq_u32 s62, s12
	v_lshl_add_u64 v[200:201], v[130:131], 0, s[24:25]
	s_cselect_b64 vcc, -1, 0
	s_add_i32 s12, s12, 2
	v_cndmask_b32_e32 v209, v201, v173, vcc
	v_cndmask_b32_e32 v208, v200, v172, vcc
	v_cndmask_b32_e32 v213, v129, v175, vcc
	v_cndmask_b32_e32 v212, v128, v174, vcc
	v_lshl_add_u64 v[214:215], v[130:131], 0, v[160:161]
	s_add_i32 m0, s41, 0xc000
	ds_read_b128 v[200:203], v216
	ds_read_b128 v[204:207], v216 offset:1024
	ds_read_b128 v[218:221], v216 offset:2048
	ds_read_b128 v[222:225], v216 offset:3072
	ds_read_b128 v[226:229], v216 offset:4096
	ds_read_b128 v[230:233], v216 offset:5120
	ds_read_b128 v[234:237], v216 offset:6144
	ds_read_b128 v[238:241], v216 offset:7168
	global_load_lds_dwordx4 v[214:215], off
	v_lshl_add_u64 v[214:215], v[130:131], 0, v[158:159]
	s_add_i32 m0, s41, 0xe000
	s_nop 0
	global_load_lds_dwordx4 v[214:215], off
	s_waitcnt vmcnt(8)
	s_waitcnt lgkmcnt(0)
	s_setprio 1
	s_barrier
	v_mfma_f32_16x16x32_bf16 v[124:127], v[132:135], v[200:203], v[124:127]
	v_mfma_f32_16x16x32_bf16 v[120:123], v[176:179], v[200:203], v[120:123]
	v_mfma_f32_16x16x32_bf16 v[108:111], v[132:135], v[218:221], v[108:111]
	v_mfma_f32_16x16x32_bf16 v[104:107], v[176:179], v[218:221], v[104:107]
	v_mfma_f32_16x16x32_bf16 v[92:95], v[132:135], v[226:229], v[92:95]
	v_mfma_f32_16x16x32_bf16 v[88:91], v[176:179], v[226:229], v[88:91]
	v_mfma_f32_16x16x32_bf16 v[76:79], v[132:135], v[234:237], v[76:79]
	v_mfma_f32_16x16x32_bf16 v[72:75], v[176:179], v[234:237], v[72:75]
	v_mfma_f32_16x16x32_bf16 v[124:127], v[136:139], v[204:207], v[124:127]
	v_mfma_f32_16x16x32_bf16 v[120:123], v[180:183], v[204:207], v[120:123]
	v_mfma_f32_16x16x32_bf16 v[108:111], v[136:139], v[222:225], v[108:111]
	v_mfma_f32_16x16x32_bf16 v[104:107], v[180:183], v[222:225], v[104:107]
	v_mfma_f32_16x16x32_bf16 v[92:95], v[136:139], v[230:233], v[92:95]
	v_mfma_f32_16x16x32_bf16 v[88:91], v[180:183], v[230:233], v[88:91]
	v_mfma_f32_16x16x32_bf16 v[76:79], v[136:139], v[238:241], v[76:79]
	v_mfma_f32_16x16x32_bf16 v[72:75], v[180:183], v[238:241], v[72:75]
	s_cmp_gt_u32 s75, 3
	s_cbranch_scc1 .Lie_skipk0
	v_mfma_f32_16x16x32_bf16 v[116:119], v[184:187], v[200:203], v[116:119]
	v_mfma_f32_16x16x32_bf16 v[112:115], v[192:195], v[200:203], v[112:115]
	v_mfma_f32_16x16x32_bf16 v[100:103], v[184:187], v[218:221], v[100:103]
	v_mfma_f32_16x16x32_bf16 v[96:99], v[192:195], v[218:221], v[96:99]
	v_mfma_f32_16x16x32_bf16 v[84:87], v[184:187], v[226:229], v[84:87]
	v_mfma_f32_16x16x32_bf16 v[80:83], v[192:195], v[226:229], v[80:83]
	v_mfma_f32_16x16x32_bf16 v[68:71], v[184:187], v[234:237], v[68:71]
	v_mfma_f32_16x16x32_bf16 v[64:67], v[192:195], v[234:237], v[64:67]
	v_mfma_f32_16x16x32_bf16 v[116:119], v[188:191], v[204:207], v[116:119]
	v_mfma_f32_16x16x32_bf16 v[112:115], v[196:199], v[204:207], v[112:115]
	v_mfma_f32_16x16x32_bf16 v[100:103], v[188:191], v[222:225], v[100:103]
	v_mfma_f32_16x16x32_bf16 v[96:99], v[196:199], v[222:225], v[96:99]
	v_mfma_f32_16x16x32_bf16 v[84:87], v[188:191], v[230:233], v[84:87]
	v_mfma_f32_16x16x32_bf16 v[80:83], v[196:199], v[230:233], v[80:83]
	v_mfma_f32_16x16x32_bf16 v[68:71], v[188:191], v[238:241], v[68:71]
	v_mfma_f32_16x16x32_bf16 v[64:67], v[196:199], v[238:241], v[64:67]
.Lie_skipk0:
	s_setprio 0
	s_barrier
	s_add_i32 s13, s69, s37
	v_lshl_add_u64 v[214:215], v[212:213], 0, v[146:147]
	s_mov_b32 m0, s13
	ds_read_b128 v[200:203], v216 offset:16384
	ds_read_b128 v[204:207], v216 offset:17408
	ds_read_b128 v[218:221], v216 offset:18432
	ds_read_b128 v[222:225], v216 offset:19456
	ds_read_b128 v[226:229], v216 offset:20480
	ds_read_b128 v[230:233], v216 offset:21504
	ds_read_b128 v[234:237], v216 offset:22528
	ds_read_b128 v[238:241], v216 offset:23552
	global_load_lds_dwordx4 v[214:215], off
	v_lshl_add_u64 v[242:243], v[212:213], 0, v[150:151]
	s_add_i32 m0, s13, 0x2000
	v_lshl_add_u64 v[212:213], v[212:213], 0, s[16:17]
	s_add_i32 s13, s70, s37
	global_load_lds_dwordx4 v[242:243], off
	v_lshl_add_u64 v[244:245], v[212:213], 0, v[146:147]
	s_mov_b32 m0, s13
	v_lshl_add_u64 v[212:213], v[212:213], 0, v[150:151]
	global_load_lds_dwordx4 v[244:245], off
	s_add_i32 m0, s13, 0x2000
	v_lshl_add_u64 v[246:247], v[208:209], 0, v[144:145]
	global_load_lds_dwordx4 v[212:213], off
	s_mov_b32 m0, s41
	v_lshl_add_u64 v[248:249], v[208:209], 0, v[148:149]
	global_load_lds_dwordx4 v[246:247], off
	s_mov_b32 m0, s50
	s_nop 0
	global_load_lds_dwordx4 v[248:249], off
	s_waitcnt vmcnt(8)
	s_waitcnt lgkmcnt(0)
	s_setprio 1
	s_barrier
	v_mfma_f32_16x16x32_bf16 v[60:63], v[132:135], v[200:203], v[60:63]
	v_mfma_f32_16x16x32_bf16 v[56:59], v[176:179], v[200:203], v[56:59]
	v_mfma_f32_16x16x32_bf16 v[44:47], v[132:135], v[218:221], v[44:47]
	v_mfma_f32_16x16x32_bf16 v[40:43], v[176:179], v[218:221], v[40:43]
	v_mfma_f32_16x16x32_bf16 v[28:31], v[132:135], v[226:229], v[28:31]
	v_mfma_f32_16x16x32_bf16 v[24:27], v[176:179], v[226:229], v[24:27]
	v_mfma_f32_16x16x32_bf16 v[12:15], v[132:135], v[234:237], v[12:15]
	v_mfma_f32_16x16x32_bf16 v[8:11], v[176:179], v[234:237], v[8:11]
	v_mfma_f32_16x16x32_bf16 v[60:63], v[136:139], v[204:207], v[60:63]
	v_mfma_f32_16x16x32_bf16 v[56:59], v[180:183], v[204:207], v[56:59]
	v_mfma_f32_16x16x32_bf16 v[44:47], v[136:139], v[222:225], v[44:47]
	v_mfma_f32_16x16x32_bf16 v[40:43], v[180:183], v[222:225], v[40:43]
	v_mfma_f32_16x16x32_bf16 v[28:31], v[136:139], v[230:233], v[28:31]
	v_mfma_f32_16x16x32_bf16 v[24:27], v[180:183], v[230:233], v[24:27]
	v_mfma_f32_16x16x32_bf16 v[12:15], v[136:139], v[238:241], v[12:15]
	v_mfma_f32_16x16x32_bf16 v[8:11], v[180:183], v[238:241], v[8:11]
	s_cmp_gt_u32 s75, 3
	s_cbranch_scc1 .Lie_skipk1
; #define PG8_STAGE(bufoff, gbase, voff) do { _Pragma("unroll") for (int _i = 0; _i < 2; ++_i) \
;         __builtin_amdgcn_global_load_lds((const unsigned*)((const char*)(gbase) + (voff)[_i]), (PG8_LAS unsigned*)(lds + (bufoff) + ldsw + _i * 8192), 16, 0, 0); } while (0)
; #define PG8_LDA(dst, b, h) do { _Pragma("unroll") for (int m = 0; m < 4; ++m) _Pragma("unroll") for (int k = 0; k < 2; ++k) dst[m][k] = *(const PG8_LAS bf16x8*)(lds + PG8_SA(b, h) + aoff + m * 2048 + k * 1024); } while (0)
; #define PG8_LDB(dst, b, h) do { _Pragma("unroll") for (int n = 0; n < 2; ++n) _Pragma("unroll") for (int k = 0; k < 2; ++k) dst[n][k] = *(const PG8_LAS bf16x8*)(lds + PG8_SB(b, h) + boff + n * 2048 + k * 1024); } while (0)
; #define PG8_MMA(ai, bj, At, Bt) do { __builtin_amdgcn_s_setprio(1); _Pragma("unroll") for (int m = 0; m < 4; ++m) _Pragma("unroll") for (int n = 0; n < 2; ++n) _Pragma("unroll") for (int k = 0; k < 2; ++k) \
;         acc[ai][bj][m][n] = __builtin_amdgcn_mfma_f32_16x16x32_bf16(Bt[n][k], At[m][k], acc[ai][bj][m][n], 0, 0, 0); __builtin_amdgcn_s_setprio(0); } while (0)
; #define PG8_WAIT_V(n) asm volatile("s_waitcnt vmcnt(" #n ")" ::: "memory")
; #define PG8_WAIT_L(n) asm volatile("s_waitcnt lgkmcnt(" #n ")" ::: "memory")
; #define PG8_BAR __builtin_amdgcn_s_barrier()
; #define PG8_SCHED __builtin_amdgcn_sched_barrier(0)
; template <class Epi, class Sched, bool ALIGN_EPI = false, bool SP2 = false>
; __device__ __forceinline__ void gemm_phase(PG8_LAS unsigned char* lds, const Gemm g, const Sched& S, const Epi& E) {
;     ...
;             PG8_WAIT_V(8); PG8_WAIT_L(0); PG8_BAR; PG8_MMA(1, 0, At, B0); PG8_MMA(1, 1, At, B1); PG8_BAR; PG8_SCHED;
;             PG8_LDB(B0, 1, 0); PG8_LDB(B1, 1, 1); PG8_SCHED; PG8_LDA(At, 1, 0); PG8_STAGE(PG8_SA(0, 1), a2 + hstep, voffA);
;             PG8_WAIT_V(8); PG8_WAIT_L(0); PG8_BAR; PG8_MMA(0, 0, At, B0); PG8_MMA(0, 1, At, B1); PG8_BAR; PG8_SCHED;
	v_mfma_f32_16x16x32_bf16 v[52:55], v[184:187], v[200:203], v[52:55]
	v_mfma_f32_16x16x32_bf16 v[48:51], v[192:195], v[200:203], v[48:51]
	v_mfma_f32_16x16x32_bf16 v[36:39], v[184:187], v[218:221], v[36:39]
	v_mfma_f32_16x16x32_bf16 v[32:35], v[192:195], v[218:221], v[32:35]
	v_mfma_f32_16x16x32_bf16 v[20:23], v[184:187], v[226:229], v[20:23]
	v_mfma_f32_16x16x32_bf16 v[16:19], v[192:195], v[226:229], v[16:19]
	v_mfma_f32_16x16x32_bf16 v[4:7], v[184:187], v[234:237], v[4:7]
	v_mfma_f32_16x16x32_bf16 v[0:3], v[192:195], v[234:237], v[0:3]
	v_mfma_f32_16x16x32_bf16 v[52:55], v[188:191], v[204:207], v[52:55]
	v_mfma_f32_16x16x32_bf16 v[48:51], v[196:199], v[204:207], v[48:51]
	v_mfma_f32_16x16x32_bf16 v[36:39], v[188:191], v[222:225], v[36:39]
	v_mfma_f32_16x16x32_bf16 v[32:35], v[196:199], v[222:225], v[32:35]
	v_mfma_f32_16x16x32_bf16 v[20:23], v[188:191], v[230:233], v[20:23]
	v_mfma_f32_16x16x32_bf16 v[16:19], v[196:199], v[230:233], v[16:19]
	v_mfma_f32_16x16x32_bf16 v[4:7], v[188:191], v[238:241], v[4:7]
	v_mfma_f32_16x16x32_bf16 v[0:3], v[196:199], v[238:241], v[0:3]
.Lie_skipk1:
	s_setprio 0
	s_barrier
	s_add_i32 s13, 0, 0x18000
	v_add_u32_e32 v165, s13, v171
	s_add_i32 s15, 0, 0x1c000
	ds_read_b128 v[132:135], v165
	ds_read_b128 v[136:139], v165 offset:1024
	ds_read_b128 v[176:179], v165 offset:2048
	ds_read_b128 v[180:183], v165 offset:3072
	v_add_u32_e32 v165, s15, v171
	ds_read_b128 v[184:187], v165
	ds_read_b128 v[188:191], v165 offset:1024
	ds_read_b128 v[192:195], v165 offset:2048
	ds_read_b128 v[196:199], v165 offset:3072
	v_lshl_add_u64 v[208:209], v[208:209], 0, s[16:17]
	s_mov_b32 m0, s52
	v_lshl_add_u64 v[250:251], v[208:209], 0, v[144:145]
	ds_read_b128 v[200:203], v216 offset:32768
	ds_read_b128 v[204:207], v216 offset:33792
	ds_read_b128 v[218:221], v216 offset:34816
	ds_read_b128 v[222:225], v216 offset:35840
	ds_read_b128 v[226:229], v216 offset:36864
	ds_read_b128 v[230:233], v216 offset:37888
	ds_read_b128 v[234:237], v216 offset:38912
	ds_read_b128 v[238:241], v216 offset:39936
	global_load_lds_dwordx4 v[250:251], off
	v_lshl_add_u64 v[208:209], v[208:209], 0, v[148:149]
	s_mov_b32 m0, s53
	s_nop 0
	global_load_lds_dwordx4 v[208:209], off
	s_waitcnt vmcnt(8)
	s_waitcnt lgkmcnt(0)
	s_setprio 1
	s_barrier
	v_mfma_f32_16x16x32_bf16 v[124:127], v[132:135], v[200:203], v[124:127]
	v_mfma_f32_16x16x32_bf16 v[120:123], v[176:179], v[200:203], v[120:123]
	v_mfma_f32_16x16x32_bf16 v[108:111], v[132:135], v[218:221], v[108:111]
	v_mfma_f32_16x16x32_bf16 v[104:107], v[176:179], v[218:221], v[104:107]
	v_mfma_f32_16x16x32_bf16 v[92:95], v[132:135], v[226:229], v[92:95]
	v_mfma_f32_16x16x32_bf16 v[88:91], v[176:179], v[226:229], v[88:91]
	v_mfma_f32_16x16x32_bf16 v[76:79], v[132:135], v[234:237], v[76:79]
	v_mfma_f32_16x16x32_bf16 v[72:75], v[176:179], v[234:237], v[72:75]
	v_mfma_f32_16x16x32_bf16 v[124:127], v[136:139], v[204:207], v[124:127]
	v_mfma_f32_16x16x32_bf16 v[120:123], v[180:183], v[204:207], v[120:123]
	v_mfma_f32_16x16x32_bf16 v[108:111], v[136:139], v[222:225], v[108:111]
	v_mfma_f32_16x16x32_bf16 v[104:107], v[180:183], v[222:225], v[104:107]
	v_mfma_f32_16x16x32_bf16 v[92:95], v[136:139], v[230:233], v[92:95]
	v_mfma_f32_16x16x32_bf16 v[88:91], v[180:183], v[230:233], v[88:91]
	v_mfma_f32_16x16x32_bf16 v[76:79], v[136:139], v[238:241], v[76:79]
	v_mfma_f32_16x16x32_bf16 v[72:75], v[180:183], v[238:241], v[72:75]
	s_cmp_gt_u32 s75, 3
	s_cbranch_scc1 .Lie_skipk2
	v_mfma_f32_16x16x32_bf16 v[116:119], v[184:187], v[200:203], v[116:119]
	v_mfma_f32_16x16x32_bf16 v[112:115], v[192:195], v[200:203], v[112:115]
	v_mfma_f32_16x16x32_bf16 v[100:103], v[184:187], v[218:221], v[100:103]
	v_mfma_f32_16x16x32_bf16 v[96:99], v[192:195], v[218:221], v[96:99]
	v_mfma_f32_16x16x32_bf16 v[84:87], v[184:187], v[226:229], v[84:87]
	v_mfma_f32_16x16x32_bf16 v[80:83], v[192:195], v[226:229], v[80:83]
	v_mfma_f32_16x16x32_bf16 v[68:71], v[184:187], v[234:237], v[68:71]
	v_mfma_f32_16x16x32_bf16 v[64:67], v[192:195], v[234:237], v[64:67]
	v_mfma_f32_16x16x32_bf16 v[116:119], v[188:191], v[204:207], v[116:119]
	v_mfma_f32_16x16x32_bf16 v[112:115], v[196:199], v[204:207], v[112:115]
	v_mfma_f32_16x16x32_bf16 v[100:103], v[188:191], v[222:225], v[100:103]
	v_mfma_f32_16x16x32_bf16 v[96:99], v[196:199], v[222:225], v[96:99]
	v_mfma_f32_16x16x32_bf16 v[84:87], v[188:191], v[230:233], v[84:87]
	v_mfma_f32_16x16x32_bf16 v[80:83], v[196:199], v[230:233], v[80:83]
	v_mfma_f32_16x16x32_bf16 v[68:71], v[188:191], v[238:241], v[68:71]
	v_mfma_f32_16x16x32_bf16 v[64:67], v[196:199], v[238:241], v[64:67]
; #define PG8_STAGE(bufoff, gbase, voff) do { _Pragma("unroll") for (int _i = 0; _i < 2; ++_i) \
;         __builtin_amdgcn_global_load_lds((const unsigned*)((const char*)(gbase) + (voff)[_i]), (PG8_LAS unsigned*)(lds + (bufoff) + ldsw + _i * 8192), 16, 0, 0); } while (0)
; #define PG8_LDA(dst, b, h) do { _Pragma("unroll") for (int m = 0; m < 4; ++m) _Pragma("unroll") for (int k = 0; k < 2; ++k) dst[m][k] = *(const PG8_LAS bf16x8*)(lds + PG8_SA(b, h) + aoff + m * 2048 + k * 1024); } while (0)
; #define PG8_MMA(ai, bj, At, Bt) do { __builtin_amdgcn_s_setprio(1); _Pragma("unroll") for (int m = 0; m < 4; ++m) _Pragma("unroll") for (int n = 0; n < 2; ++n) _Pragma("unroll") for (int k = 0; k < 2; ++k) \
;         acc[ai][bj][m][n] = __builtin_amdgcn_mfma_f32_16x16x32_bf16(Bt[n][k], At[m][k], acc[ai][bj][m][n], 0, 0, 0); __builtin_amdgcn_s_setprio(0); } while (0)
; #define PG8_WAIT_V(n) asm volatile("s_waitcnt vmcnt(" #n ")" ::: "memory")
; #define PG8_WAIT_L(n) asm volatile("s_waitcnt lgkmcnt(" #n ")" ::: "memory")
; #define PG8_BAR __builtin_amdgcn_s_barrier()
; #define PG8_SCHED __builtin_amdgcn_sched_barrier(0)
; template <class Epi, class Sched, bool ALIGN_EPI = false, bool SP2 = false>
; __device__ __forceinline__ void gemm_phase(PG8_LAS unsigned char* lds, const Gemm g, const Sched& S, const Epi& E) {
;     ...
;             PG8_WAIT_V(8); PG8_WAIT_L(0); PG8_BAR; PG8_MMA(0, 0, At, B0); PG8_MMA(0, 1, At, B1); PG8_BAR; PG8_SCHED;
;             PG8_LDA(At, 1, 1); PG8_STAGE(PG8_SB(1, 0), b3, voffB); PG8_STAGE(PG8_SB(1, 1), b3 + hstep, voffB); PG8_STAGE(PG8_SA(1, 0), a3, voffA);
;             PG8_WAIT_V(8); PG8_WAIT_L(0); PG8_BAR; PG8_MMA(1, 0, At, B0); PG8_MMA(1, 1, At, B1); PG8_BAR; PG8_SCHED;
.Lie_skipk2:
	s_setprio 0
	s_barrier
	s_add_i32 s13, s13, s37
	v_lshl_add_u64 v[208:209], v[214:215], 0, s[24:25]
	s_mov_b32 m0, s13
	ds_read_b128 v[200:203], v216 offset:49152
	ds_read_b128 v[204:207], v216 offset:50176
	ds_read_b128 v[218:221], v216 offset:51200
	ds_read_b128 v[222:225], v216 offset:52224
	ds_read_b128 v[226:229], v216 offset:53248
	ds_read_b128 v[230:233], v216 offset:54272
	ds_read_b128 v[234:237], v216 offset:55296
	ds_read_b128 v[238:241], v216 offset:56320
	global_load_lds_dwordx4 v[208:209], off
	v_lshl_add_u64 v[208:209], v[242:243], 0, s[24:25]
	s_add_i32 m0, s13, 0x2000
	s_add_i32 s13, s15, s37
	global_load_lds_dwordx4 v[208:209], off
	v_lshl_add_u64 v[208:209], v[244:245], 0, s[24:25]
	s_mov_b32 m0, s13
	s_nop 0
	global_load_lds_dwordx4 v[208:209], off
	v_lshl_add_u64 v[208:209], v[212:213], 0, s[24:25]
	s_add_i32 m0, s13, 0x2000
	s_nop 0
	global_load_lds_dwordx4 v[208:209], off
	v_lshl_add_u64 v[208:209], v[246:247], 0, s[24:25]
	s_mov_b32 m0, s56
	s_nop 0
	global_load_lds_dwordx4 v[208:209], off
	v_lshl_add_u64 v[208:209], v[248:249], 0, s[24:25]
	s_mov_b32 m0, s57
	s_nop 0
	global_load_lds_dwordx4 v[208:209], off
	s_waitcnt vmcnt(8)
	s_waitcnt lgkmcnt(0)
	s_setprio 1
	s_barrier
	v_mfma_f32_16x16x32_bf16 v[60:63], v[132:135], v[200:203], v[60:63]
	v_mfma_f32_16x16x32_bf16 v[56:59], v[176:179], v[200:203], v[56:59]
	v_mfma_f32_16x16x32_bf16 v[44:47], v[132:135], v[218:221], v[44:47]
	v_mfma_f32_16x16x32_bf16 v[40:43], v[176:179], v[218:221], v[40:43]
	v_mfma_f32_16x16x32_bf16 v[28:31], v[132:135], v[226:229], v[28:31]
	v_mfma_f32_16x16x32_bf16 v[24:27], v[176:179], v[226:229], v[24:27]
	v_mfma_f32_16x16x32_bf16 v[12:15], v[132:135], v[234:237], v[12:15]
	v_mfma_f32_16x16x32_bf16 v[8:11], v[176:179], v[234:237], v[8:11]
	v_mfma_f32_16x16x32_bf16 v[60:63], v[136:139], v[204:207], v[60:63]
	v_mfma_f32_16x16x32_bf16 v[56:59], v[180:183], v[204:207], v[56:59]
	v_mfma_f32_16x16x32_bf16 v[44:47], v[136:139], v[222:225], v[44:47]
	v_mfma_f32_16x16x32_bf16 v[40:43], v[180:183], v[222:225], v[40:43]
	v_mfma_f32_16x16x32_bf16 v[28:31], v[136:139], v[230:233], v[28:31]
	v_mfma_f32_16x16x32_bf16 v[24:27], v[180:183], v[230:233], v[24:27]
	v_mfma_f32_16x16x32_bf16 v[12:15], v[136:139], v[238:241], v[12:15]
	v_mfma_f32_16x16x32_bf16 v[8:11], v[180:183], v[238:241], v[8:11]
	s_cmp_gt_u32 s75, 3
	s_cbranch_scc1 .Lie_skipk3
	v_mfma_f32_16x16x32_bf16 v[52:55], v[184:187], v[200:203], v[52:55]
	v_mfma_f32_16x16x32_bf16 v[48:51], v[192:195], v[200:203], v[48:51]
	v_mfma_f32_16x16x32_bf16 v[36:39], v[184:187], v[218:221], v[36:39]
	v_mfma_f32_16x16x32_bf16 v[32:35], v[192:195], v[218:221], v[32:35]
	v_mfma_f32_16x16x32_bf16 v[20:23], v[184:187], v[226:229], v[20:23]
	v_mfma_f32_16x16x32_bf16 v[16:19], v[192:195], v[226:229], v[16:19]
	v_mfma_f32_16x16x32_bf16 v[4:7], v[184:187], v[234:237], v[4:7]
	v_mfma_f32_16x16x32_bf16 v[0:3], v[192:195], v[234:237], v[0:3]
	v_mfma_f32_16x16x32_bf16 v[52:55], v[188:191], v[204:207], v[52:55]
	v_mfma_f32_16x16x32_bf16 v[48:51], v[196:199], v[204:207], v[48:51]
	v_mfma_f32_16x16x32_bf16 v[36:39], v[188:191], v[222:225], v[36:39]
	v_mfma_f32_16x16x32_bf16 v[32:35], v[196:199], v[222:225], v[32:35]
	v_mfma_f32_16x16x32_bf16 v[20:23], v[188:191], v[230:233], v[20:23]
	v_mfma_f32_16x16x32_bf16 v[16:19], v[196:199], v[230:233], v[16:19]
	v_mfma_f32_16x16x32_bf16 v[4:7], v[188:191], v[238:241], v[4:7]
	v_mfma_f32_16x16x32_bf16 v[0:3], v[196:199], v[238:241], v[0:3]
.Lie_skipk3:
	s_setprio 0
	s_barrier
	v_lshl_add_u64 v[128:129], v[128:129], 0, s[34:35]
	s_cmp_ge_i32 s12, s58
	v_lshl_add_u64 v[130:131], v[130:131], 0, s[34:35]
	s_cbranch_scc0 .LBB0_454

; template <class Epi, class Sched, bool ALIGN_EPI = false, bool SP2 = false>
; __device__ __forceinline__ void gemm_phase(PG8_LAS unsigned char* lds, const Gemm g, const Sched& S, const Epi& E) {
;     ...
;         for (int t = 0; t < nt; t += 2) {
;             const bool last = (t == nt - 2);
;             const char* a1 = cA + (size_t)(t + 1) * kstep;
;             const char* a2 = last ? nA : cA + (size_t)(t + 2) * kstep; const char* b2 = last ? nB : cB + (size_t)(t + 2) * kstep;
;     ...
; #pragma unroll
;         for (int a = 0; a < 2; ++a)
; #pragma unroll
;             for (int b = 0; b < 2; ++b)
; #pragma unroll
;                 for (int m = 0; m < 4; ++m)
; #pragma unroll
;                     for (int n = 0; n < 2; ++n) acc[a][b][m][n] = (f32x4){0.f, 0.f, 0.f, 0.f};
;         cur = nxt; cA = nA; cB = nB; ++ui;
.LBB0_633:
	v_mov_b32_e32 v143, 0
	s_andn2_b64 vcc, exec, s[26:27]
	v_mov_b32_e32 v142, v143
	v_mov_b32_e32 v141, v143
	v_mov_b32_e32 v140, v143
	v_mov_b32_e32 v139, v143
	v_mov_b32_e32 v138, v143
	v_mov_b32_e32 v137, v143
	v_mov_b32_e32 v136, v143
	v_mov_b32_e32 v119, v143
	v_mov_b32_e32 v118, v143
	v_mov_b32_e32 v117, v143
	v_mov_b32_e32 v116, v143
	v_mov_b32_e32 v115, v143
	v_mov_b32_e32 v114, v143
	v_mov_b32_e32 v113, v143
	v_mov_b32_e32 v112, v143
	v_mov_b32_e32 v103, v143
	v_mov_b32_e32 v102, v143
	v_mov_b32_e32 v101, v143
	v_mov_b32_e32 v100, v143
	v_mov_b32_e32 v99, v143
	v_mov_b32_e32 v98, v143
	v_mov_b32_e32 v97, v143
	v_mov_b32_e32 v96, v143
	v_mov_b32_e32 v79, v143
	v_mov_b32_e32 v78, v143
	v_mov_b32_e32 v77, v143
	v_mov_b32_e32 v76, v143
	v_mov_b32_e32 v75, v143
	v_mov_b32_e32 v74, v143
	v_mov_b32_e32 v73, v143
	v_mov_b32_e32 v72, v143
	v_mov_b32_e32 v127, v143
	v_mov_b32_e32 v126, v143
	v_mov_b32_e32 v125, v143
	v_mov_b32_e32 v124, v143
	v_mov_b32_e32 v123, v143
	v_mov_b32_e32 v122, v143
	v_mov_b32_e32 v121, v143
	v_mov_b32_e32 v120, v143
	v_mov_b32_e32 v111, v143
	v_mov_b32_e32 v110, v143
	v_mov_b32_e32 v109, v143
	v_mov_b32_e32 v108, v143
	v_mov_b32_e32 v107, v143
	v_mov_b32_e32 v106, v143
	v_mov_b32_e32 v105, v143
	v_mov_b32_e32 v104, v143
	v_mov_b32_e32 v87, v143
	v_mov_b32_e32 v86, v143
	v_mov_b32_e32 v85, v143
	v_mov_b32_e32 v84, v143
	v_mov_b32_e32 v83, v143
	v_mov_b32_e32 v82, v143
	v_mov_b32_e32 v81, v143
	v_mov_b32_e32 v80, v143
	v_mov_b32_e32 v71, v143
	v_mov_b32_e32 v70, v143
	v_mov_b32_e32 v69, v143
	v_mov_b32_e32 v68, v143
	v_mov_b32_e32 v67, v143
	v_mov_b32_e32 v66, v143
	v_mov_b32_e32 v65, v143
	v_mov_b32_e32 v64, v143
	v_mov_b32_e32 v63, v143
	v_mov_b32_e32 v62, v143
	v_mov_b32_e32 v61, v143
	v_mov_b32_e32 v60, v143
	v_mov_b32_e32 v59, v143
	v_mov_b32_e32 v58, v143
	v_mov_b32_e32 v57, v143
	v_mov_b32_e32 v56, v143
	v_mov_b32_e32 v47, v143
	v_mov_b32_e32 v46, v143
	v_mov_b32_e32 v45, v143
	v_mov_b32_e32 v44, v143
	v_mov_b32_e32 v43, v143
	v_mov_b32_e32 v42, v143
	v_mov_b32_e32 v41, v143
	v_mov_b32_e32 v40, v143
	v_mov_b32_e32 v31, v143
	v_mov_b32_e32 v30, v143
	v_mov_b32_e32 v29, v143
	v_mov_b32_e32 v28, v143
	v_mov_b32_e32 v27, v143
	v_mov_b32_e32 v26, v143
	v_mov_b32_e32 v25, v143
	v_mov_b32_e32 v24, v143
	v_mov_b32_e32 v15, v143
	v_mov_b32_e32 v14, v143
	v_mov_b32_e32 v13, v143
	v_mov_b32_e32 v12, v143
	v_mov_b32_e32 v11, v143
	v_mov_b32_e32 v10, v143
	v_mov_b32_e32 v9, v143
	v_mov_b32_e32 v8, v143
	v_mov_b32_e32 v55, v143
	v_mov_b32_e32 v54, v143
	v_mov_b32_e32 v53, v143
	v_mov_b32_e32 v52, v143
	v_mov_b32_e32 v51, v143
	v_mov_b32_e32 v50, v143
	v_mov_b32_e32 v49, v143
	v_mov_b32_e32 v48, v143
	v_mov_b32_e32 v39, v143
	v_mov_b32_e32 v38, v143
	v_mov_b32_e32 v37, v143
	v_mov_b32_e32 v36, v143
	v_mov_b32_e32 v35, v143
	v_mov_b32_e32 v34, v143
	v_mov_b32_e32 v33, v143
	v_mov_b32_e32 v32, v143
	v_mov_b32_e32 v23, v143
	v_mov_b32_e32 v22, v143
	v_mov_b32_e32 v21, v143
	v_mov_b32_e32 v20, v143
	v_mov_b32_e32 v19, v143
	v_mov_b32_e32 v18, v143
	v_mov_b32_e32 v17, v143
	v_mov_b32_e32 v16, v143
	v_mov_b32_e32 v7, v143
	v_mov_b32_e32 v6, v143
	v_mov_b32_e32 v5, v143
	v_mov_b32_e32 v4, v143
	v_mov_b32_e32 v3, v143
	v_mov_b32_e32 v2, v143
	v_mov_b32_e32 v1, v143
	v_mov_b32_e32 v0, v143
	s_cbranch_vccnz .LBB0_636
	v_mov_b32_e32 v0, 0
	v_lshl_add_u64 v[88:89], v[88:89], 0, s[30:31]
	v_lshl_add_u64 v[90:91], v[90:91], 0, s[24:25]
	s_mov_b32 s10, 0
	v_mov_b32_e32 v1, v0
	v_mov_b32_e32 v2, v0
	v_mov_b32_e32 v3, v0
	v_mov_b32_e32 v4, v0
	v_mov_b32_e32 v5, v0
	v_mov_b32_e32 v6, v0
	v_mov_b32_e32 v7, v0
	v_mov_b32_e32 v16, v0
	v_mov_b32_e32 v17, v0
	v_mov_b32_e32 v18, v0
	v_mov_b32_e32 v19, v0
	v_mov_b32_e32 v20, v0
	v_mov_b32_e32 v21, v0
	v_mov_b32_e32 v22, v0
	v_mov_b32_e32 v23, v0
	v_mov_b32_e32 v32, v0
	v_mov_b32_e32 v33, v0
	v_mov_b32_e32 v34, v0
	v_mov_b32_e32 v35, v0
	v_mov_b32_e32 v36, v0
	v_mov_b32_e32 v37, v0
	v_mov_b32_e32 v38, v0
	v_mov_b32_e32 v39, v0
	v_mov_b32_e32 v48, v0
	v_mov_b32_e32 v49, v0
	v_mov_b32_e32 v50, v0
	v_mov_b32_e32 v51, v0
	v_mov_b32_e32 v52, v0
	v_mov_b32_e32 v53, v0
	v_mov_b32_e32 v54, v0
	v_mov_b32_e32 v55, v0
	v_mov_b32_e32 v8, v0
	v_mov_b32_e32 v9, v0
	v_mov_b32_e32 v10, v0
	v_mov_b32_e32 v11, v0
	v_mov_b32_e32 v12, v0
	v_mov_b32_e32 v13, v0
	v_mov_b32_e32 v14, v0
	v_mov_b32_e32 v15, v0
	v_mov_b32_e32 v24, v0
	v_mov_b32_e32 v25, v0
	v_mov_b32_e32 v26, v0
	v_mov_b32_e32 v27, v0
	v_mov_b32_e32 v28, v0
	v_mov_b32_e32 v29, v0
	v_mov_b32_e32 v30, v0
	v_mov_b32_e32 v31, v0
	v_mov_b32_e32 v40, v0
	v_mov_b32_e32 v41, v0
	v_mov_b32_e32 v42, v0
	v_mov_b32_e32 v43, v0
	v_mov_b32_e32 v44, v0
	v_mov_b32_e32 v45, v0
	v_mov_b32_e32 v46, v0
	v_mov_b32_e32 v47, v0
	v_mov_b32_e32 v56, v0
	v_mov_b32_e32 v57, v0
	v_mov_b32_e32 v58, v0
	v_mov_b32_e32 v59, v0
	v_mov_b32_e32 v60, v0
	v_mov_b32_e32 v61, v0
	v_mov_b32_e32 v62, v0
	v_mov_b32_e32 v63, v0
	v_mov_b32_e32 v64, v0
	v_mov_b32_e32 v65, v0
	v_mov_b32_e32 v66, v0
	v_mov_b32_e32 v67, v0
	v_mov_b32_e32 v68, v0
	v_mov_b32_e32 v69, v0
	v_mov_b32_e32 v70, v0
	v_mov_b32_e32 v71, v0
	v_mov_b32_e32 v80, v0
	v_mov_b32_e32 v81, v0
	v_mov_b32_e32 v82, v0
	v_mov_b32_e32 v83, v0
	v_mov_b32_e32 v84, v0
	v_mov_b32_e32 v85, v0
	v_mov_b32_e32 v86, v0
	v_mov_b32_e32 v87, v0
	v_mov_b32_e32 v104, v0
	v_mov_b32_e32 v105, v0
	v_mov_b32_e32 v106, v0
	v_mov_b32_e32 v107, v0
	v_mov_b32_e32 v108, v0
	v_mov_b32_e32 v109, v0
	v_mov_b32_e32 v110, v0
	v_mov_b32_e32 v111, v0
	v_mov_b32_e32 v120, v0
	v_mov_b32_e32 v121, v0
	v_mov_b32_e32 v122, v0
	v_mov_b32_e32 v123, v0
	v_mov_b32_e32 v124, v0
	v_mov_b32_e32 v125, v0
	v_mov_b32_e32 v126, v0
	v_mov_b32_e32 v127, v0
	v_mov_b32_e32 v72, v0
	v_mov_b32_e32 v73, v0
	v_mov_b32_e32 v74, v0
	v_mov_b32_e32 v75, v0
	v_mov_b32_e32 v76, v0
	v_mov_b32_e32 v77, v0
	v_mov_b32_e32 v78, v0
	v_mov_b32_e32 v79, v0
	v_mov_b32_e32 v96, v0
	v_mov_b32_e32 v97, v0
	v_mov_b32_e32 v98, v0
	v_mov_b32_e32 v99, v0
	v_mov_b32_e32 v100, v0
	v_mov_b32_e32 v101, v0
	v_mov_b32_e32 v102, v0
	v_mov_b32_e32 v103, v0
	v_mov_b32_e32 v112, v0
	v_mov_b32_e32 v113, v0
	v_mov_b32_e32 v114, v0
	v_mov_b32_e32 v115, v0
	v_mov_b32_e32 v116, v0
	v_mov_b32_e32 v117, v0
	v_mov_b32_e32 v118, v0
	v_mov_b32_e32 v119, v0
	v_mov_b32_e32 v136, v0
	v_mov_b32_e32 v137, v0
	v_mov_b32_e32 v138, v0
	v_mov_b32_e32 v139, v0
	v_mov_b32_e32 v140, v0
	v_mov_b32_e32 v141, v0
	v_mov_b32_e32 v142, v0
	v_mov_b32_e32 v143, v0
	.p2align	6

; template <class Epi, class Sched, bool ALIGN_EPI = false, bool SP2 = false>
; __device__ __forceinline__ void gemm_phase(PG8_LAS unsigned char* lds, const Gemm g, const Sched& S, const Epi& E) {
;     ...
;         for (int t = 0; t < nt; t += 2) {
;             const bool last = (t == nt - 2);
;             const char* a1 = cA + (size_t)(t + 1) * kstep;
;             const char* a2 = last ? nA : cA + (size_t)(t + 2) * kstep; const char* b2 = last ? nB : cB + (size_t)(t + 2) * kstep;
;     ...
; #pragma unroll
;         for (int a = 0; a < 2; ++a)
; #pragma unroll
;             for (int b = 0; b < 2; ++b)
; #pragma unroll
;                 for (int m = 0; m < 4; ++m)
; #pragma unroll
;                     for (int n = 0; n < 2; ++n) acc[a][b][m][n] = (f32x4){0.f, 0.f, 0.f, 0.f};
;         cur = nxt; cA = nA; cB = nB; ++ui;
.LBB0_720:
	v_mov_b32_e32 v135, 0
	s_andn2_b64 vcc, exec, s[20:21]
	v_mov_b32_e32 v134, v135
	v_mov_b32_e32 v133, v135
	v_mov_b32_e32 v132, v135
	v_mov_b32_e32 v131, v135
	v_mov_b32_e32 v130, v135
	v_mov_b32_e32 v129, v135
	v_mov_b32_e32 v128, v135
	v_mov_b32_e32 v111, v135
	v_mov_b32_e32 v110, v135
	v_mov_b32_e32 v109, v135
	v_mov_b32_e32 v108, v135
	v_mov_b32_e32 v107, v135
	v_mov_b32_e32 v106, v135
	v_mov_b32_e32 v105, v135
	v_mov_b32_e32 v104, v135
	v_mov_b32_e32 v95, v135
	v_mov_b32_e32 v94, v135
	v_mov_b32_e32 v93, v135
	v_mov_b32_e32 v92, v135
	v_mov_b32_e32 v91, v135
	v_mov_b32_e32 v90, v135
	v_mov_b32_e32 v89, v135
	v_mov_b32_e32 v88, v135
	v_mov_b32_e32 v79, v135
	v_mov_b32_e32 v78, v135
	v_mov_b32_e32 v77, v135
	v_mov_b32_e32 v76, v135
	v_mov_b32_e32 v75, v135
	v_mov_b32_e32 v74, v135
	v_mov_b32_e32 v73, v135
	v_mov_b32_e32 v72, v135
	v_mov_b32_e32 v127, v135
	v_mov_b32_e32 v126, v135
	v_mov_b32_e32 v125, v135
	v_mov_b32_e32 v124, v135
	v_mov_b32_e32 v123, v135
	v_mov_b32_e32 v122, v135
	v_mov_b32_e32 v121, v135
	v_mov_b32_e32 v120, v135
	v_mov_b32_e32 v103, v135
	v_mov_b32_e32 v102, v135
	v_mov_b32_e32 v101, v135
	v_mov_b32_e32 v100, v135
	v_mov_b32_e32 v99, v135
	v_mov_b32_e32 v98, v135
	v_mov_b32_e32 v97, v135
	v_mov_b32_e32 v96, v135
	v_mov_b32_e32 v87, v135
	v_mov_b32_e32 v86, v135
	v_mov_b32_e32 v85, v135
	v_mov_b32_e32 v84, v135
	v_mov_b32_e32 v83, v135
	v_mov_b32_e32 v82, v135
	v_mov_b32_e32 v81, v135
	v_mov_b32_e32 v80, v135
	v_mov_b32_e32 v71, v135
	v_mov_b32_e32 v70, v135
	v_mov_b32_e32 v69, v135
	v_mov_b32_e32 v68, v135
	v_mov_b32_e32 v67, v135
	v_mov_b32_e32 v66, v135
	v_mov_b32_e32 v65, v135
	v_mov_b32_e32 v64, v135
	v_mov_b32_e32 v63, v135
	v_mov_b32_e32 v62, v135
	v_mov_b32_e32 v61, v135
	v_mov_b32_e32 v60, v135
	v_mov_b32_e32 v59, v135
	v_mov_b32_e32 v58, v135
	v_mov_b32_e32 v57, v135
	v_mov_b32_e32 v56, v135
	v_mov_b32_e32 v47, v135
	v_mov_b32_e32 v46, v135
	v_mov_b32_e32 v45, v135
	v_mov_b32_e32 v44, v135
	v_mov_b32_e32 v43, v135
	v_mov_b32_e32 v42, v135
	v_mov_b32_e32 v41, v135
	v_mov_b32_e32 v40, v135
	v_mov_b32_e32 v31, v135
	v_mov_b32_e32 v30, v135
	v_mov_b32_e32 v29, v135
	v_mov_b32_e32 v28, v135
	v_mov_b32_e32 v27, v135
	v_mov_b32_e32 v26, v135
	v_mov_b32_e32 v25, v135
	v_mov_b32_e32 v24, v135
	v_mov_b32_e32 v15, v135
	v_mov_b32_e32 v14, v135
	v_mov_b32_e32 v13, v135
	v_mov_b32_e32 v12, v135
	v_mov_b32_e32 v11, v135
	v_mov_b32_e32 v10, v135
	v_mov_b32_e32 v9, v135
	v_mov_b32_e32 v8, v135
	v_mov_b32_e32 v55, v135
	v_mov_b32_e32 v54, v135
	v_mov_b32_e32 v53, v135
	v_mov_b32_e32 v52, v135
	v_mov_b32_e32 v51, v135
	v_mov_b32_e32 v50, v135
	v_mov_b32_e32 v49, v135
	v_mov_b32_e32 v48, v135
	v_mov_b32_e32 v39, v135
	v_mov_b32_e32 v38, v135
	v_mov_b32_e32 v37, v135
	v_mov_b32_e32 v36, v135
	v_mov_b32_e32 v35, v135
	v_mov_b32_e32 v34, v135
	v_mov_b32_e32 v33, v135
	v_mov_b32_e32 v32, v135
	v_mov_b32_e32 v23, v135
	v_mov_b32_e32 v22, v135
	v_mov_b32_e32 v21, v135
	v_mov_b32_e32 v20, v135
	v_mov_b32_e32 v19, v135
	v_mov_b32_e32 v18, v135
	v_mov_b32_e32 v17, v135
	v_mov_b32_e32 v16, v135
	v_mov_b32_e32 v7, v135
	v_mov_b32_e32 v6, v135
	v_mov_b32_e32 v5, v135
	v_mov_b32_e32 v4, v135
	v_mov_b32_e32 v3, v135
	v_mov_b32_e32 v2, v135
	v_mov_b32_e32 v1, v135
	v_mov_b32_e32 v0, v135
	s_cbranch_vccnz .LBB0_723
	v_mov_b32_e32 v0, 0
	v_lshl_add_u64 v[112:113], v[112:113], 0, s[26:27]
	v_lshl_add_u64 v[114:115], v[114:115], 0, s[18:19]
	s_mov_b32 s8, 0
	v_mov_b32_e32 v1, v0
	v_mov_b32_e32 v2, v0
	v_mov_b32_e32 v3, v0
	v_mov_b32_e32 v4, v0
	v_mov_b32_e32 v5, v0
	v_mov_b32_e32 v6, v0
	v_mov_b32_e32 v7, v0
	v_mov_b32_e32 v16, v0
	v_mov_b32_e32 v17, v0
	v_mov_b32_e32 v18, v0
	v_mov_b32_e32 v19, v0
	v_mov_b32_e32 v20, v0
	v_mov_b32_e32 v21, v0
	v_mov_b32_e32 v22, v0
	v_mov_b32_e32 v23, v0
	v_mov_b32_e32 v32, v0
	v_mov_b32_e32 v33, v0
	v_mov_b32_e32 v34, v0
	v_mov_b32_e32 v35, v0
	v_mov_b32_e32 v36, v0
	v_mov_b32_e32 v37, v0
	v_mov_b32_e32 v38, v0
	v_mov_b32_e32 v39, v0
	v_mov_b32_e32 v48, v0
	v_mov_b32_e32 v49, v0
	v_mov_b32_e32 v50, v0
	v_mov_b32_e32 v51, v0
	v_mov_b32_e32 v52, v0
	v_mov_b32_e32 v53, v0
	v_mov_b32_e32 v54, v0
	v_mov_b32_e32 v55, v0
	v_mov_b32_e32 v8, v0
	v_mov_b32_e32 v9, v0
	v_mov_b32_e32 v10, v0
	v_mov_b32_e32 v11, v0
	v_mov_b32_e32 v12, v0
	v_mov_b32_e32 v13, v0
	v_mov_b32_e32 v14, v0
	v_mov_b32_e32 v15, v0
	v_mov_b32_e32 v24, v0
	v_mov_b32_e32 v25, v0
	v_mov_b32_e32 v26, v0
	v_mov_b32_e32 v27, v0
	v_mov_b32_e32 v28, v0
	v_mov_b32_e32 v29, v0
	v_mov_b32_e32 v30, v0
	v_mov_b32_e32 v31, v0
	v_mov_b32_e32 v40, v0
	v_mov_b32_e32 v41, v0
	v_mov_b32_e32 v42, v0
	v_mov_b32_e32 v43, v0
	v_mov_b32_e32 v44, v0
	v_mov_b32_e32 v45, v0
	v_mov_b32_e32 v46, v0
	v_mov_b32_e32 v47, v0
	v_mov_b32_e32 v56, v0
	v_mov_b32_e32 v57, v0
	v_mov_b32_e32 v58, v0
	v_mov_b32_e32 v59, v0
	v_mov_b32_e32 v60, v0
	v_mov_b32_e32 v61, v0
	v_mov_b32_e32 v62, v0
	v_mov_b32_e32 v63, v0
	v_mov_b32_e32 v64, v0
	v_mov_b32_e32 v65, v0
	v_mov_b32_e32 v66, v0
	v_mov_b32_e32 v67, v0
	v_mov_b32_e32 v68, v0
	v_mov_b32_e32 v69, v0
	v_mov_b32_e32 v70, v0
	v_mov_b32_e32 v71, v0
	v_mov_b32_e32 v80, v0
	v_mov_b32_e32 v81, v0
	v_mov_b32_e32 v82, v0
	v_mov_b32_e32 v83, v0
	v_mov_b32_e32 v84, v0
	v_mov_b32_e32 v85, v0
	v_mov_b32_e32 v86, v0
	v_mov_b32_e32 v87, v0
	v_mov_b32_e32 v96, v0
	v_mov_b32_e32 v97, v0
	v_mov_b32_e32 v98, v0
	v_mov_b32_e32 v99, v0
	v_mov_b32_e32 v100, v0
	v_mov_b32_e32 v101, v0
	v_mov_b32_e32 v102, v0
	v_mov_b32_e32 v103, v0
	v_mov_b32_e32 v120, v0
	v_mov_b32_e32 v121, v0
	v_mov_b32_e32 v122, v0
	v_mov_b32_e32 v123, v0
	v_mov_b32_e32 v124, v0
	v_mov_b32_e32 v125, v0
	v_mov_b32_e32 v126, v0
	v_mov_b32_e32 v127, v0
	v_mov_b32_e32 v72, v0
	v_mov_b32_e32 v73, v0
	v_mov_b32_e32 v74, v0
	v_mov_b32_e32 v75, v0
	v_mov_b32_e32 v76, v0
	v_mov_b32_e32 v77, v0
	v_mov_b32_e32 v78, v0
	v_mov_b32_e32 v79, v0
	v_mov_b32_e32 v88, v0
	v_mov_b32_e32 v89, v0
	v_mov_b32_e32 v90, v0
	v_mov_b32_e32 v91, v0
	v_mov_b32_e32 v92, v0
	v_mov_b32_e32 v93, v0
	v_mov_b32_e32 v94, v0
	v_mov_b32_e32 v95, v0
	v_mov_b32_e32 v104, v0
	v_mov_b32_e32 v105, v0
	v_mov_b32_e32 v106, v0
	v_mov_b32_e32 v107, v0
	v_mov_b32_e32 v108, v0
	v_mov_b32_e32 v109, v0
	v_mov_b32_e32 v110, v0
	v_mov_b32_e32 v111, v0
	v_mov_b32_e32 v128, v0
	v_mov_b32_e32 v129, v0
	v_mov_b32_e32 v130, v0
	v_mov_b32_e32 v131, v0
	v_mov_b32_e32 v132, v0
	v_mov_b32_e32 v133, v0
	v_mov_b32_e32 v134, v0
	v_mov_b32_e32 v135, v0
	.p2align	6

; template <int MODE>
; __device__ __forceinline__ void attn_unit(const Params& P, int b, int h, int qb, unsigned char* smem) {
;     ...
;         for (int a = 0; a < 4; ++a) {
;           bf16x8 vf = *(const bf16x8*)(smem + cur + 8192 + (32 * db + r) * 128 + (((2 * a + hi) ^ swz) << 4));
;           oacc[db] = __builtin_amdgcn_mfma_f32_32x32x16_bf16(vf, pf[a], oacc[db], 0, 0, 0);
;         }
;     }
;     if (more) sstore(nxt);
;     __syncthreads();
;   }
.LBB0_845:
	s_or_b64 exec, exec, s[16:17]
	s_add_i32 s27, s27, 1
	s_add_i32 s10, s10, 64
	v_lshl_add_u64 v[86:87], v[86:87], 0, s[12:13]
	s_cmp_eq_u32 s26, s27
	v_lshl_add_u64 v[88:89], v[88:89], 0, s[14:15]
	s_waitcnt lgkmcnt(0)
	s_barrier
	s_cbranch_scc1 .LBB0_856
	.p2align	6

; #define GAS __attribute__((address_space(1)))
; template <int MODE>
; __device__ __forceinline__ void attn_unit(const Params& P, int b, int h, int qb, unsigned char* smem) {
;   const int tid = tid_fresh(), lane = tid & 63, w = tid >> 6, r = lane & 31, hi = lane >> 5;
;   constexpr int NKS = (MODE == 0) ? 6 : 4;
;   const bf16_t *Q, *K, *Kr = nullptr, *Vt; bf16_t* O; int ldq, ldk; const float* cb = nullptr;
;   float slope2 = 0.f, m_run = -1e30f, l_run = 0.f;
;   if (MODE == 0) {
;     Q = P.Qb + (size_t)b * SEQ * 768 + h * 96; ldq = 768; K = P.Kn + (size_t)b * SEQ * 512 + h * 64; ldk = 512;
;     Kr = P.Kr + (size_t)b * SEQ * 32; Vt = P.Vtb + (size_t)(b * 8 + h) * 64 * SEQ; O = P.mix + (size_t)b * SEQ * 1024 + 512 + h * 64;
;   } else if (MODE == 1) {
;     Q = P.Qc + (size_t)b * SEQ * 1024 + h * 64; ldq = 1024; K = P.Kc + (size_t)b * SEQ * 1024 + h * 64; ldk = 1024;
;     Vt = P.Vtc + (size_t)(b * 16 + h) * 64 * SEQ; O = P.Qc + (size_t)b * SEQ * 1024 + h * 64; cb = P.logc + (size_t)(b * 16 + h) * SEQ;
;   } else {
;     Q = P.Qa + (size_t)b * SEQ * 512 + h * 64; ldq = 512; K = P.Ka + (size_t)b * SEQ * 128 + (h >> 2) * 64; ldk = 128;
;     Vt = P.Vta + (size_t)(b * 2 + (h >> 2)) * 64 * SEQ; O = P.mix + (size_t)b * SEQ * 1024 + h * 64;
;     slope2 = exp2f(-(float)(h + 1)) * LOG2E;
;     m_run = ((GAS const float*)P.ev_sinks)[h] * LOG2E; l_run = hi ? 0.f : 1.f;
;   }
;   const int q0 = qb * 256, qw0 = q0 + 32 * w, qi = qw0 + r;
;   bf16x8 qf[NKS];
; #pragma unroll
;   for (int ks = 0; ks < NKS; ++ks) qf[ks] = *(GAS const bf16x8*)(Q + (size_t)qi * ldq + 16 * ks + 8 * hi);
;   f32x16 oacc[2];
; #pragma unroll
;   for (int i = 0; i < 16; ++i) { oacc[0][i] = 0.f; oacc[1][i] = 0.f; }
;   const int kt_end = 4 * qb + 4;
;   const int kt_beg = (MODE == 2) ? (qb > 0 ? 4 * qb - 2 : 0) : 0;
;   const int srow = tid >> 3, sch = tid & 7;
;   const unsigned soff = srow * 128 + ((sch ^ ((srow >> 1) & 7)) << 4);
;   const int rrow = (tid & 255) >> 2, rch = tid & 3;
;   const unsigned roff = 16384u + rrow * 64 + ((rch ^ ((rrow >> 2) & 3)) << 4);
;   constexpr unsigned BUFSZ = 20736u;
;   u32x4 rk, rv, rr_; f32x4 rc;
;   auto gload = [&](int kt) {
;     const int k0 = kt * 64;
;     rk = *(GAS const u32x4*)(K + (size_t)(k0 + srow) * ldk + sch * 8);
;     rv = *(GAS const u32x4*)(Vt + (size_t)srow * SEQ + k0 + sch * 8);
.LBB0_868:
	v_mov_b32_e32 v9, v254
	v_mov_b64_e32 v[2:3], s[8:9]
	flat_load_dwordx2 v[4:5], v[2:3] offset:440
	flat_load_dwordx2 v[6:7], v[2:3] offset:456
	flat_load_dwordx2 v[12:13], v[2:3] offset:480
	flat_load_dwordx2 v[14:15], v[2:3] offset:104
	s_bfe_u32 s23, s21, 0x30003
	v_ashrrev_i32_e32 v0, 1, v9
	s_ashr_i32 s14, s21, 6
	s_and_b32 s22, s21, 7
	s_lshl_b32 s10, s23, 22
	v_and_b32_e32 v10, 0xffffffe0, v0
	s_bfe_u32 s15, s21, 0x10002
	v_and_b32_e32 v8, 31, v9
	v_lshl_add_u32 v10, s14, 8, v10
	s_lshl_b32 s12, s15, 7
	s_lshl_b32 s15, s15, 19
	s_lshl_b32 s16, s14, 2
	v_or_b32_e32 v106, v10, v8
	s_lshl_b32 s6, s22, 2
	s_add_i32 s24, s16, 4
	s_add_i32 s16, s16, -2
	v_ashrrev_i32_e32 v107, 31, v106
	s_mov_b32 s7, s11
	flat_load_dwordx2 v[104:105], v[2:3] offset:496
	v_bfe_u32 v175, v9, 5, 1
	v_ashrrev_i32_e32 v2, 3, v9
	v_lshlrev_b32_e32 v3, 3, v9
	v_lshlrev_b64 v[18:19], 10, v[106:107]
	s_mov_b32 s13, s11
	v_lshlrev_b32_e32 v0, 4, v175
	v_and_b32_e32 v11, 56, v3
	v_ashrrev_i32_e32 v3, 31, v2
	v_lshlrev_b64 v[16:17], 13, v[2:3]
	v_cmp_eq_u32_e32 vcc, 0, v175
	s_waitcnt vmcnt(0) lgkmcnt(0)
	v_lshl_add_u64 v[4:5], v[4:5], 0, s[10:11]
	s_lshl_b32 s10, s22, 7
	v_lshl_add_u64 v[4:5], v[4:5], 0, s[10:11]
	s_lshl_b32 s10, s23, 20
	v_lshl_add_u64 v[6:7], v[6:7], 0, s[10:11]
	s_or_b32 s10, s15, s10
	s_cmp_gt_i32 s14, 0
	v_lshl_add_u64 v[14:15], v[14:15], 0, s[6:7]
	v_lshl_add_u64 v[4:5], v[4:5], 0, v[18:19]
	s_cselect_b32 s6, s16, 0
	global_load_dword v3, v[14:15], off
	v_lshl_add_u64 v[14:15], v[4:5], 0, v[0:1]
	v_lshl_add_u64 v[6:7], v[6:7], 0, s[12:13]
	v_lshl_add_u64 v[4:5], v[12:13], 0, s[10:11]
	s_lshl_b32 s12, s6, 6
	v_lshl_add_u64 v[4:5], v[4:5], 0, v[16:17]
	s_ashr_i32 s13, s12, 31
	v_lshlrev_b32_e32 v0, 1, v11
	v_lshl_add_u64 v[16:17], s[12:13], 1, v[4:5]
	v_add_u32_e32 v12, s12, v2
	v_lshl_add_u64 v[16:17], v[16:17], 0, v[0:1]
	v_ashrrev_i32_e32 v13, 31, v12
	global_load_dwordx4 v[96:99], v[16:17], off
	v_lshlrev_b64 v[12:13], 8, v[12:13]
	v_lshl_add_u64 v[12:13], v[6:7], 0, v[12:13]
	v_lshl_add_u64 v[12:13], v[12:13], 0, v[0:1]
	global_load_dwordx4 v[100:103], v[12:13], off
	global_load_dwordx4 v[80:83], v[14:15], off
	global_load_dwordx4 v[84:87], v[14:15], off offset:32
	global_load_dwordx4 v[88:91], v[14:15], off offset:64
	global_load_dwordx4 v[92:95], v[14:15], off offset:96
	v_lshlrev_b32_e32 v11, 4, v9
	v_lshlrev_b32_e32 v12, 7, v2
	v_xor_b32_e32 v11, v11, v9
	v_and_or_b32 v11, v11, s18, v12
	v_cndmask_b32_e64 v176, 0, 1.0, vcc
	v_add_u32_e32 v177, 0, v11
	s_cmp_ge_i32 s6, s24
	s_waitcnt vmcnt(5)
	ds_write_b128 v177, v[96:99] offset:8192
	s_waitcnt vmcnt(4)
	ds_write_b128 v177, v[100:103]
	s_waitcnt lgkmcnt(0)
	s_barrier
	s_cbranch_scc1 .LBB0_866
	s_add_i32 s7, s22, 1
	v_lshl_add_u64 v[108:109], v[6:7], 0, v[0:1]
	v_cvt_f32_ubyte0_e32 v6, s7
	v_cmp_lt_f32_e32 vcc, s19, v6
	s_and_b64 s[14:15], vcc, exec
	s_cselect_b32 s7, 0xffffffc0, 0
	v_cndmask_b32_e32 v7, 0, v148, vcc
	v_sub_f32_e32 v6, v7, v6
	v_exp_f32_e32 v6, v6
	v_lshl_add_u64 v[110:111], v[4:5], 0, v[0:1]
	v_bfe_u32 v4, v9, 1, 3
	v_mov_b32_e32 v14, v1
	v_ldexp_f32 v0, v6, s7
	v_mul_f32_e32 v112, 0x3fb8aa3b, v0
	v_lshrrev_b32_e32 v0, 1, v9
	v_bitop3_b32 v0, v175, v0, 7 bitop3:0x78
	v_lshlrev_b32_e32 v180, 4, v0
	v_bitop3_b32 v0, v175, v4, 2 bitop3:0x36
	v_lshlrev_b32_e32 v181, 4, v0
	v_bitop3_b32 v0, v175, v4, 4 bitop3:0x36
	v_lshlrev_b32_e32 v182, 4, v0
	v_bitop3_b32 v0, v175, v4, 6 bitop3:0x36
	v_lshlrev_b32_e32 v183, 4, v0
	v_add_u32_e32 v0, v10, v8
	v_mov_b32_e32 v15, v1
	v_mul_f32_e32 v146, 0x3fb8aa3b, v3
	v_or_b32_e32 v178, 31, v10
	v_add_u32_e32 v179, 0xffffff80, v10
	v_lshl_add_u32 v184, v8, 7, 0
	v_subrev_u32_e32 v185, s12, v0
	v_add_u32_e32 v186, 64, v2
	v_mov_b32_e32 v0, v1
	v_mov_b32_e32 v2, v1
	v_mov_b32_e32 v3, v1
	v_mov_b32_e32 v4, v1
	v_mov_b32_e32 v5, v1
	v_mov_b32_e32 v6, v1
	v_mov_b32_e32 v7, v1
	v_mov_b32_e32 v8, v1
	v_mov_b32_e32 v9, v1
	v_mov_b32_e32 v10, v1
	v_mov_b32_e32 v11, v1
	v_mov_b32_e32 v12, v1
	v_mov_b32_e32 v13, v1
	v_mov_b64_e32 v[46:47], v[14:15]
	v_mov_b64_e32 v[30:31], v[14:15]
	v_mul_i32_i24_e32 v114, -4, v175
	v_mad_i32_i24 v115, v175, -4, -1
	v_mad_i32_i24 v117, v175, -4, -3
	v_mad_i32_i24 v116, v175, -4, -2
	v_mad_i32_i24 v119, v175, -4, -9
	v_mad_i32_i24 v118, v175, -4, -8
	v_mad_i32_i24 v121, v175, -4, -11
	v_mad_i32_i24 v120, v175, -4, -10
	v_mad_i32_i24 v123, v175, -4, v149
	v_mad_i32_i24 v122, v175, -4, -16
	v_mad_i32_i24 v125, v175, -4, v150
	v_mad_i32_i24 v124, v175, -4, v151
	v_mad_i32_i24 v127, v175, -4, v152
	v_mad_i32_i24 v126, v175, -4, v153
	v_mad_i32_i24 v129, v175, -4, v154
	v_mad_i32_i24 v128, v175, -4, v155
	v_mad_i32_i24 v131, v175, -4, v158
	v_mad_i32_i24 v130, v175, -4, v159
	v_mad_i32_i24 v133, v175, -4, v160
	v_mad_i32_i24 v132, v175, -4, v161
	v_mad_i32_i24 v135, v175, -4, v162
	v_mad_i32_i24 v134, v175, -4, v163
	v_mad_i32_i24 v137, v175, -4, v164
	v_mad_i32_i24 v136, v175, -4, v165
	v_mad_i32_i24 v139, v175, -4, v166
	v_mad_i32_i24 v138, v175, -4, v167
	v_mad_i32_i24 v141, v175, -4, v168
	v_mad_i32_i24 v140, v175, -4, v169
	v_mad_i32_i24 v143, v175, -4, v170
	v_mad_i32_i24 v142, v175, -4, v171
	v_mad_i32_i24 v145, v175, -4, v172
	v_mad_i32_i24 v144, v175, -4, v173
	v_mov_b32_e32 v113, v112
	v_mov_b64_e32 v[44:45], v[12:13]
	v_mov_b64_e32 v[42:43], v[10:11]
	v_mov_b64_e32 v[40:41], v[8:9]
	v_mov_b64_e32 v[38:39], v[6:7]
	v_mov_b64_e32 v[36:37], v[4:5]
	v_mov_b64_e32 v[34:35], v[2:3]
	v_mov_b64_e32 v[32:33], v[0:1]
	v_mov_b64_e32 v[28:29], v[12:13]
	v_mov_b64_e32 v[26:27], v[10:11]
	v_mov_b64_e32 v[24:25], v[8:9]
	v_mov_b64_e32 v[22:23], v[6:7]
	v_mov_b64_e32 v[20:21], v[4:5]
	v_mov_b64_e32 v[18:19], v[2:3]
	v_mov_b64_e32 v[16:17], v[0:1]
	.p2align	6

; template <class Epi, class Sched, bool ALIGN_EPI = false, bool SP2 = false>
; __device__ __forceinline__ void gemm_phase(PG8_LAS unsigned char* lds, const Gemm g, const Sched& S, const Epi& E) {
;     ...
;     f32x4 acc[2][2][4][2];
; #pragma unroll
;     for (int a = 0; a < 2; ++a)
; #pragma unroll
;         for (int b = 0; b < 2; ++b)
; #pragma unroll
;             for (int m = 0; m < 4; ++m)
; #pragma unroll
;                 for (int n = 0; n < 2; ++n) acc[a][b][m][n] = (f32x4){0.f, 0.f, 0.f, 0.f};
;     ...
;         if (!has_next) break;
; #pragma unroll
;         for (int a = 0; a < 2; ++a)
; #pragma unroll
;             for (int b = 0; b < 2; ++b)
; #pragma unroll
;                 for (int m = 0; m < 4; ++m)
; #pragma unroll
;                     for (int n = 0; n < 2; ++n) acc[a][b][m][n] = (f32x4){0.f, 0.f, 0.f, 0.f};
;         cur = nxt; cA = nA; cB = nB; ++ui;
.LBB0_938:
	v_mov_b32_e32 v123, 0
	s_and_b64 vcc, exec, s[8:9]
	v_mov_b32_e32 v122, v123
	v_mov_b32_e32 v121, v123
	v_mov_b32_e32 v120, v123
	v_mov_b32_e32 v127, v123
	v_mov_b32_e32 v126, v123
	v_mov_b32_e32 v125, v123
	v_mov_b32_e32 v124, v123
	v_mov_b32_e32 v111, v123
	v_mov_b32_e32 v110, v123
	v_mov_b32_e32 v109, v123
	v_mov_b32_e32 v108, v123
	v_mov_b32_e32 v107, v123
	v_mov_b32_e32 v106, v123
	v_mov_b32_e32 v105, v123
	v_mov_b32_e32 v104, v123
	v_mov_b32_e32 v95, v123
	v_mov_b32_e32 v94, v123
	v_mov_b32_e32 v93, v123
	v_mov_b32_e32 v92, v123
	v_mov_b32_e32 v91, v123
	v_mov_b32_e32 v90, v123
	v_mov_b32_e32 v89, v123
	v_mov_b32_e32 v88, v123
	v_mov_b32_e32 v79, v123
	v_mov_b32_e32 v78, v123
	v_mov_b32_e32 v77, v123
	v_mov_b32_e32 v76, v123
	v_mov_b32_e32 v75, v123
	v_mov_b32_e32 v74, v123
	v_mov_b32_e32 v73, v123
	v_mov_b32_e32 v72, v123
	v_mov_b32_e32 v119, v123
	v_mov_b32_e32 v118, v123
	v_mov_b32_e32 v117, v123
	v_mov_b32_e32 v116, v123
	v_mov_b32_e32 v115, v123
	v_mov_b32_e32 v114, v123
	v_mov_b32_e32 v113, v123
	v_mov_b32_e32 v112, v123
	v_mov_b32_e32 v103, v123
	v_mov_b32_e32 v102, v123
	v_mov_b32_e32 v101, v123
	v_mov_b32_e32 v100, v123
	v_mov_b32_e32 v99, v123
	v_mov_b32_e32 v98, v123
	v_mov_b32_e32 v97, v123
	v_mov_b32_e32 v96, v123
	v_mov_b32_e32 v87, v123
	v_mov_b32_e32 v86, v123
	v_mov_b32_e32 v85, v123
	v_mov_b32_e32 v84, v123
	v_mov_b32_e32 v83, v123
	v_mov_b32_e32 v82, v123
	v_mov_b32_e32 v81, v123
	v_mov_b32_e32 v80, v123
	v_mov_b32_e32 v71, v123
	v_mov_b32_e32 v70, v123
	v_mov_b32_e32 v69, v123
	v_mov_b32_e32 v68, v123
	v_mov_b32_e32 v67, v123
	v_mov_b32_e32 v66, v123
	v_mov_b32_e32 v65, v123
	v_mov_b32_e32 v64, v123
	v_mov_b32_e32 v63, v123
	v_mov_b32_e32 v62, v123
	v_mov_b32_e32 v61, v123
	v_mov_b32_e32 v60, v123
	v_mov_b32_e32 v59, v123
	v_mov_b32_e32 v58, v123
	v_mov_b32_e32 v57, v123
	v_mov_b32_e32 v56, v123
	v_mov_b32_e32 v47, v123
	v_mov_b32_e32 v46, v123
	v_mov_b32_e32 v45, v123
	v_mov_b32_e32 v44, v123
	v_mov_b32_e32 v43, v123
	v_mov_b32_e32 v42, v123
	v_mov_b32_e32 v41, v123
	v_mov_b32_e32 v40, v123
	v_mov_b32_e32 v31, v123
	v_mov_b32_e32 v30, v123
	v_mov_b32_e32 v29, v123
	v_mov_b32_e32 v28, v123
	v_mov_b32_e32 v27, v123
	v_mov_b32_e32 v26, v123
	v_mov_b32_e32 v25, v123
	v_mov_b32_e32 v24, v123
	v_mov_b32_e32 v15, v123
	v_mov_b32_e32 v14, v123
	v_mov_b32_e32 v13, v123
	v_mov_b32_e32 v12, v123
	v_mov_b32_e32 v11, v123
	v_mov_b32_e32 v10, v123
	v_mov_b32_e32 v9, v123
	v_mov_b32_e32 v8, v123
	v_mov_b32_e32 v55, v123
	v_mov_b32_e32 v54, v123
	v_mov_b32_e32 v53, v123
	v_mov_b32_e32 v52, v123
	v_mov_b32_e32 v51, v123
	v_mov_b32_e32 v50, v123
	v_mov_b32_e32 v49, v123
	v_mov_b32_e32 v48, v123
	v_mov_b32_e32 v39, v123
	v_mov_b32_e32 v38, v123
	v_mov_b32_e32 v37, v123
	v_mov_b32_e32 v36, v123
	v_mov_b32_e32 v35, v123
	v_mov_b32_e32 v34, v123
	v_mov_b32_e32 v33, v123
	v_mov_b32_e32 v32, v123
	v_mov_b32_e32 v23, v123
	v_mov_b32_e32 v22, v123
	v_mov_b32_e32 v21, v123
	v_mov_b32_e32 v20, v123
	v_mov_b32_e32 v19, v123
	v_mov_b32_e32 v18, v123
	v_mov_b32_e32 v17, v123
	v_mov_b32_e32 v16, v123
	v_mov_b32_e32 v7, v123
	v_mov_b32_e32 v6, v123
	v_mov_b32_e32 v5, v123
	v_mov_b32_e32 v4, v123
	v_mov_b32_e32 v3, v123
	v_mov_b32_e32 v2, v123
	s_waitcnt lgkmcnt(0)
	v_mov_b32_e32 v1, v123
	v_mov_b32_e32 v0, v123
	s_cbranch_vccnz .LBB0_941
	v_mov_b32_e32 v0, 0
	v_lshl_add_u64 v[128:129], v[128:129], 0, s[26:27]
	v_lshl_add_u64 v[130:131], v[130:131], 0, s[22:23]
	s_mov_b32 s12, 0
	v_mov_b32_e32 v1, v0
	v_mov_b32_e32 v2, v0
	v_mov_b32_e32 v3, v0
	v_mov_b32_e32 v4, v0
	v_mov_b32_e32 v5, v0
	v_mov_b32_e32 v6, v0
	v_mov_b32_e32 v7, v0
	v_mov_b32_e32 v16, v0
	v_mov_b32_e32 v17, v0
	v_mov_b32_e32 v18, v0
	v_mov_b32_e32 v19, v0
	v_mov_b32_e32 v20, v0
	v_mov_b32_e32 v21, v0
	v_mov_b32_e32 v22, v0
	v_mov_b32_e32 v23, v0
	v_mov_b32_e32 v32, v0
	v_mov_b32_e32 v33, v0
	v_mov_b32_e32 v34, v0
	v_mov_b32_e32 v35, v0
	v_mov_b32_e32 v36, v0
	v_mov_b32_e32 v37, v0
	v_mov_b32_e32 v38, v0
	v_mov_b32_e32 v39, v0
	v_mov_b32_e32 v48, v0
	v_mov_b32_e32 v49, v0
	v_mov_b32_e32 v50, v0
	v_mov_b32_e32 v51, v0
	v_mov_b32_e32 v52, v0
	v_mov_b32_e32 v53, v0
	v_mov_b32_e32 v54, v0
	v_mov_b32_e32 v55, v0
	v_mov_b32_e32 v8, v0
	v_mov_b32_e32 v9, v0
	v_mov_b32_e32 v10, v0
	v_mov_b32_e32 v11, v0
	v_mov_b32_e32 v12, v0
	v_mov_b32_e32 v13, v0
	v_mov_b32_e32 v14, v0
	v_mov_b32_e32 v15, v0
	v_mov_b32_e32 v24, v0
	v_mov_b32_e32 v25, v0
	v_mov_b32_e32 v26, v0
	v_mov_b32_e32 v27, v0
	v_mov_b32_e32 v28, v0
	v_mov_b32_e32 v29, v0
	v_mov_b32_e32 v30, v0
	v_mov_b32_e32 v31, v0
	v_mov_b32_e32 v40, v0
	v_mov_b32_e32 v41, v0
	v_mov_b32_e32 v42, v0
	v_mov_b32_e32 v43, v0
	v_mov_b32_e32 v44, v0
	v_mov_b32_e32 v45, v0
	v_mov_b32_e32 v46, v0
	v_mov_b32_e32 v47, v0
	v_mov_b32_e32 v56, v0
	v_mov_b32_e32 v57, v0
	v_mov_b32_e32 v58, v0
	v_mov_b32_e32 v59, v0
	v_mov_b32_e32 v60, v0
	v_mov_b32_e32 v61, v0
	v_mov_b32_e32 v62, v0
	v_mov_b32_e32 v63, v0
	v_mov_b32_e32 v64, v0
	v_mov_b32_e32 v65, v0
	v_mov_b32_e32 v66, v0
	v_mov_b32_e32 v67, v0
	v_mov_b32_e32 v68, v0
	v_mov_b32_e32 v69, v0
	v_mov_b32_e32 v70, v0
	v_mov_b32_e32 v71, v0
	v_mov_b32_e32 v80, v0
	v_mov_b32_e32 v81, v0
	v_mov_b32_e32 v82, v0
	v_mov_b32_e32 v83, v0
	v_mov_b32_e32 v84, v0
	v_mov_b32_e32 v85, v0
	v_mov_b32_e32 v86, v0
	v_mov_b32_e32 v87, v0
	v_mov_b32_e32 v96, v0
	v_mov_b32_e32 v97, v0
	v_mov_b32_e32 v98, v0
	v_mov_b32_e32 v99, v0
	v_mov_b32_e32 v100, v0
	v_mov_b32_e32 v101, v0
	v_mov_b32_e32 v102, v0
	v_mov_b32_e32 v103, v0
	v_mov_b32_e32 v112, v0
	v_mov_b32_e32 v113, v0
	v_mov_b32_e32 v114, v0
	v_mov_b32_e32 v115, v0
	v_mov_b32_e32 v116, v0
	v_mov_b32_e32 v117, v0
	v_mov_b32_e32 v118, v0
	v_mov_b32_e32 v119, v0
	v_mov_b32_e32 v72, v0
	v_mov_b32_e32 v73, v0
	v_mov_b32_e32 v74, v0
	v_mov_b32_e32 v75, v0
	v_mov_b32_e32 v76, v0
	v_mov_b32_e32 v77, v0
	v_mov_b32_e32 v78, v0
	v_mov_b32_e32 v79, v0
	v_mov_b32_e32 v88, v0
	v_mov_b32_e32 v89, v0
	v_mov_b32_e32 v90, v0
	v_mov_b32_e32 v91, v0
	v_mov_b32_e32 v92, v0
	v_mov_b32_e32 v93, v0
	v_mov_b32_e32 v94, v0
	v_mov_b32_e32 v95, v0
	v_mov_b32_e32 v104, v0
	v_mov_b32_e32 v105, v0
	v_mov_b32_e32 v106, v0
	v_mov_b32_e32 v107, v0
	v_mov_b32_e32 v108, v0
	v_mov_b32_e32 v109, v0
	v_mov_b32_e32 v110, v0
	v_mov_b32_e32 v111, v0
	v_mov_b32_e32 v124, v0
	v_mov_b32_e32 v125, v0
	v_mov_b32_e32 v126, v0
	v_mov_b32_e32 v127, v0
	v_mov_b32_e32 v120, v0
	v_mov_b32_e32 v121, v0
	v_mov_b32_e32 v122, v0
	v_mov_b32_e32 v123, v0
	.p2align	6

; template <class Epi, class Sched, bool ALIGN_EPI = false, bool SP2 = false>
; __device__ __forceinline__ void gemm_phase(PG8_LAS unsigned char* lds, const Gemm g, const Sched& S, const Epi& E) {
;     ...
;     f32x4 acc[2][2][4][2];
; #pragma unroll
;     for (int a = 0; a < 2; ++a)
; #pragma unroll
;         for (int b = 0; b < 2; ++b)
; #pragma unroll
;             for (int m = 0; m < 4; ++m)
; #pragma unroll
;                 for (int n = 0; n < 2; ++n) acc[a][b][m][n] = (f32x4){0.f, 0.f, 0.f, 0.f};
;     ...
;         if (!has_next) break;
; #pragma unroll
;         for (int a = 0; a < 2; ++a)
; #pragma unroll
;             for (int b = 0; b < 2; ++b)
; #pragma unroll
;                 for (int m = 0; m < 4; ++m)
; #pragma unroll
;                     for (int n = 0; n < 2; ++n) acc[a][b][m][n] = (f32x4){0.f, 0.f, 0.f, 0.f};
;         cur = nxt; cA = nA; cB = nB; ++ui;
.LBB0_1167:
	v_mov_b32_e32 v127, 0
	s_and_b64 vcc, exec, s[6:7]
	v_mov_b32_e32 v126, v127
	v_mov_b32_e32 v125, v127
	v_mov_b32_e32 v124, v127
	v_mov_b32_e32 v123, v127
	v_mov_b32_e32 v122, v127
	v_mov_b32_e32 v121, v127
	v_mov_b32_e32 v120, v127
	v_mov_b32_e32 v111, v127
	v_mov_b32_e32 v110, v127
	v_mov_b32_e32 v109, v127
	v_mov_b32_e32 v108, v127
	v_mov_b32_e32 v107, v127
	v_mov_b32_e32 v106, v127
	v_mov_b32_e32 v105, v127
	v_mov_b32_e32 v104, v127
	v_mov_b32_e32 v95, v127
	v_mov_b32_e32 v94, v127
	v_mov_b32_e32 v93, v127
	v_mov_b32_e32 v92, v127
	v_mov_b32_e32 v91, v127
	v_mov_b32_e32 v90, v127
	v_mov_b32_e32 v89, v127
	v_mov_b32_e32 v88, v127
	v_mov_b32_e32 v79, v127
	v_mov_b32_e32 v78, v127
	v_mov_b32_e32 v77, v127
	v_mov_b32_e32 v76, v127
	v_mov_b32_e32 v75, v127
	v_mov_b32_e32 v74, v127
	v_mov_b32_e32 v73, v127
	v_mov_b32_e32 v72, v127
	v_mov_b32_e32 v119, v127
	v_mov_b32_e32 v118, v127
	v_mov_b32_e32 v117, v127
	v_mov_b32_e32 v116, v127
	v_mov_b32_e32 v115, v127
	v_mov_b32_e32 v114, v127
	v_mov_b32_e32 v113, v127
	v_mov_b32_e32 v112, v127
	v_mov_b32_e32 v103, v127
	v_mov_b32_e32 v102, v127
	v_mov_b32_e32 v101, v127
	v_mov_b32_e32 v100, v127
	v_mov_b32_e32 v99, v127
	v_mov_b32_e32 v98, v127
	v_mov_b32_e32 v97, v127
	v_mov_b32_e32 v96, v127
	v_mov_b32_e32 v87, v127
	v_mov_b32_e32 v86, v127
	v_mov_b32_e32 v85, v127
	v_mov_b32_e32 v84, v127
	v_mov_b32_e32 v83, v127
	v_mov_b32_e32 v82, v127
	v_mov_b32_e32 v81, v127
	v_mov_b32_e32 v80, v127
	v_mov_b32_e32 v71, v127
	v_mov_b32_e32 v70, v127
	v_mov_b32_e32 v69, v127
	v_mov_b32_e32 v68, v127
	v_mov_b32_e32 v67, v127
	v_mov_b32_e32 v66, v127
	v_mov_b32_e32 v65, v127
	v_mov_b32_e32 v64, v127
	v_mov_b32_e32 v63, v127
	v_mov_b32_e32 v62, v127
	v_mov_b32_e32 v61, v127
	v_mov_b32_e32 v60, v127
	v_mov_b32_e32 v59, v127
	v_mov_b32_e32 v58, v127
	v_mov_b32_e32 v57, v127
	v_mov_b32_e32 v56, v127
	v_mov_b32_e32 v47, v127
	v_mov_b32_e32 v46, v127
	v_mov_b32_e32 v45, v127
	v_mov_b32_e32 v44, v127
	v_mov_b32_e32 v43, v127
	v_mov_b32_e32 v42, v127
	v_mov_b32_e32 v41, v127
	v_mov_b32_e32 v40, v127
	v_mov_b32_e32 v31, v127
	v_mov_b32_e32 v30, v127
	v_mov_b32_e32 v29, v127
	v_mov_b32_e32 v28, v127
	v_mov_b32_e32 v27, v127
	v_mov_b32_e32 v26, v127
	v_mov_b32_e32 v25, v127
	v_mov_b32_e32 v24, v127
	v_mov_b32_e32 v15, v127
	v_mov_b32_e32 v14, v127
	v_mov_b32_e32 v13, v127
	v_mov_b32_e32 v12, v127
	v_mov_b32_e32 v11, v127
	v_mov_b32_e32 v10, v127
	v_mov_b32_e32 v9, v127
	v_mov_b32_e32 v8, v127
	v_mov_b32_e32 v55, v127
	v_mov_b32_e32 v54, v127
	v_mov_b32_e32 v53, v127
	v_mov_b32_e32 v52, v127
	v_mov_b32_e32 v51, v127
	v_mov_b32_e32 v50, v127
	v_mov_b32_e32 v49, v127
	v_mov_b32_e32 v48, v127
	v_mov_b32_e32 v39, v127
	v_mov_b32_e32 v38, v127
	v_mov_b32_e32 v37, v127
	v_mov_b32_e32 v36, v127
	v_mov_b32_e32 v35, v127
	v_mov_b32_e32 v34, v127
	v_mov_b32_e32 v33, v127
	v_mov_b32_e32 v32, v127
	v_mov_b32_e32 v23, v127
	v_mov_b32_e32 v22, v127
	v_mov_b32_e32 v21, v127
	v_mov_b32_e32 v20, v127
	v_mov_b32_e32 v19, v127
	v_mov_b32_e32 v18, v127
	v_mov_b32_e32 v17, v127
	v_mov_b32_e32 v16, v127
	v_mov_b32_e32 v7, v127
	v_mov_b32_e32 v6, v127
	v_mov_b32_e32 v5, v127
	v_mov_b32_e32 v4, v127
	v_mov_b32_e32 v3, v127
	v_mov_b32_e32 v2, v127
	v_mov_b32_e32 v1, v127
	v_mov_b32_e32 v0, v127
	s_cbranch_vccnz .LBB0_1170
	v_mov_b32_e32 v0, 0
	v_lshl_add_u64 v[154:155], v[154:155], 0, s[28:29]
	v_lshl_add_u64 v[158:159], v[158:159], 0, s[24:25]
	s_mov_b32 s10, 0
	v_mov_b32_e32 v1, v0
	v_mov_b32_e32 v2, v0
	v_mov_b32_e32 v3, v0
	v_mov_b32_e32 v4, v0
	v_mov_b32_e32 v5, v0
	v_mov_b32_e32 v6, v0
	v_mov_b32_e32 v7, v0
	v_mov_b32_e32 v16, v0
	v_mov_b32_e32 v17, v0
	v_mov_b32_e32 v18, v0
	v_mov_b32_e32 v19, v0
	v_mov_b32_e32 v20, v0
	v_mov_b32_e32 v21, v0
	v_mov_b32_e32 v22, v0
	v_mov_b32_e32 v23, v0
	v_mov_b32_e32 v32, v0
	v_mov_b32_e32 v33, v0
	v_mov_b32_e32 v34, v0
	v_mov_b32_e32 v35, v0
	v_mov_b32_e32 v36, v0
	v_mov_b32_e32 v37, v0
	v_mov_b32_e32 v38, v0
	v_mov_b32_e32 v39, v0
	v_mov_b32_e32 v48, v0
	v_mov_b32_e32 v49, v0
	v_mov_b32_e32 v50, v0
	v_mov_b32_e32 v51, v0
	v_mov_b32_e32 v52, v0
	v_mov_b32_e32 v53, v0
	v_mov_b32_e32 v54, v0
	v_mov_b32_e32 v55, v0
	v_mov_b32_e32 v8, v0
	v_mov_b32_e32 v9, v0
	v_mov_b32_e32 v10, v0
	v_mov_b32_e32 v11, v0
	v_mov_b32_e32 v12, v0
	v_mov_b32_e32 v13, v0
	v_mov_b32_e32 v14, v0
	v_mov_b32_e32 v15, v0
	v_mov_b32_e32 v24, v0
	v_mov_b32_e32 v25, v0
	v_mov_b32_e32 v26, v0
	v_mov_b32_e32 v27, v0
	v_mov_b32_e32 v28, v0
	v_mov_b32_e32 v29, v0
	v_mov_b32_e32 v30, v0
	v_mov_b32_e32 v31, v0
	v_mov_b32_e32 v40, v0
	v_mov_b32_e32 v41, v0
	v_mov_b32_e32 v42, v0
	v_mov_b32_e32 v43, v0
	v_mov_b32_e32 v44, v0
	v_mov_b32_e32 v45, v0
	v_mov_b32_e32 v46, v0
	v_mov_b32_e32 v47, v0
	v_mov_b32_e32 v56, v0
	v_mov_b32_e32 v57, v0
	v_mov_b32_e32 v58, v0
	v_mov_b32_e32 v59, v0
	v_mov_b32_e32 v60, v0
	v_mov_b32_e32 v61, v0
	v_mov_b32_e32 v62, v0
	v_mov_b32_e32 v63, v0
	v_mov_b32_e32 v64, v0
	v_mov_b32_e32 v65, v0
	v_mov_b32_e32 v66, v0
	v_mov_b32_e32 v67, v0
	v_mov_b32_e32 v68, v0
	v_mov_b32_e32 v69, v0
	v_mov_b32_e32 v70, v0
	v_mov_b32_e32 v71, v0
	v_mov_b32_e32 v80, v0
	v_mov_b32_e32 v81, v0
	v_mov_b32_e32 v82, v0
	v_mov_b32_e32 v83, v0
	v_mov_b32_e32 v84, v0
	v_mov_b32_e32 v85, v0
	v_mov_b32_e32 v86, v0
	v_mov_b32_e32 v87, v0
	v_mov_b32_e32 v96, v0
	v_mov_b32_e32 v97, v0
	v_mov_b32_e32 v98, v0
	v_mov_b32_e32 v99, v0
	v_mov_b32_e32 v100, v0
	v_mov_b32_e32 v101, v0
	v_mov_b32_e32 v102, v0
	v_mov_b32_e32 v103, v0
	v_mov_b32_e32 v112, v0
	v_mov_b32_e32 v113, v0
	v_mov_b32_e32 v114, v0
	v_mov_b32_e32 v115, v0
	v_mov_b32_e32 v116, v0
	v_mov_b32_e32 v117, v0
	v_mov_b32_e32 v118, v0
	v_mov_b32_e32 v119, v0
	v_mov_b32_e32 v72, v0
	v_mov_b32_e32 v73, v0
	v_mov_b32_e32 v74, v0
	v_mov_b32_e32 v75, v0
	v_mov_b32_e32 v76, v0
	v_mov_b32_e32 v77, v0
	v_mov_b32_e32 v78, v0
	v_mov_b32_e32 v79, v0
	v_mov_b32_e32 v88, v0
	v_mov_b32_e32 v89, v0
	v_mov_b32_e32 v90, v0
	v_mov_b32_e32 v91, v0
	v_mov_b32_e32 v92, v0
	v_mov_b32_e32 v93, v0
	v_mov_b32_e32 v94, v0
	v_mov_b32_e32 v95, v0
	v_mov_b32_e32 v104, v0
	v_mov_b32_e32 v105, v0
	v_mov_b32_e32 v106, v0
	v_mov_b32_e32 v107, v0
	v_mov_b32_e32 v108, v0
	v_mov_b32_e32 v109, v0
	v_mov_b32_e32 v110, v0
	v_mov_b32_e32 v111, v0
	v_mov_b32_e32 v120, v0
	v_mov_b32_e32 v121, v0
	v_mov_b32_e32 v122, v0
	v_mov_b32_e32 v123, v0
	v_mov_b32_e32 v124, v0
	v_mov_b32_e32 v125, v0
	v_mov_b32_e32 v126, v0
	v_mov_b32_e32 v127, v0
	.p2align	6

; template <class Epi, class Sched, bool ALIGN_EPI = false, bool SP2 = false>
; __device__ __forceinline__ void gemm_phase(PG8_LAS unsigned char* lds, const Gemm g, const Sched& S, const Epi& E) {
;     ...
;     f32x4 acc[2][2][4][2];
; #pragma unroll
;     for (int a = 0; a < 2; ++a)
; #pragma unroll
;         for (int b = 0; b < 2; ++b)
; #pragma unroll
;             for (int m = 0; m < 4; ++m)
; #pragma unroll
;                 for (int n = 0; n < 2; ++n) acc[a][b][m][n] = (f32x4){0.f, 0.f, 0.f, 0.f};
;     ...
;         if (!has_next) break;
; #pragma unroll
;         for (int a = 0; a < 2; ++a)
; #pragma unroll
;             for (int b = 0; b < 2; ++b)
; #pragma unroll
;                 for (int m = 0; m < 4; ++m)
; #pragma unroll
;                     for (int n = 0; n < 2; ++n) acc[a][b][m][n] = (f32x4){0.f, 0.f, 0.f, 0.f};
;         cur = nxt; cA = nA; cB = nB; ++ui;
.LBB0_1190:
	v_mov_b32_e32 v133, 0
	s_andn2_b64 vcc, exec, s[22:23]
	v_mov_b32_e32 v132, v133
	v_mov_b32_e32 v131, v133
	v_mov_b32_e32 v130, v133
	v_mov_b32_e32 v129, v133
	v_mov_b32_e32 v128, v133
	v_mov_b32_e32 v127, v133
	v_mov_b32_e32 v126, v133
	v_mov_b32_e32 v117, v133
	v_mov_b32_e32 v116, v133
	v_mov_b32_e32 v115, v133
	v_mov_b32_e32 v114, v133
	v_mov_b32_e32 v113, v133
	v_mov_b32_e32 v112, v133
	v_mov_b32_e32 v111, v133
	v_mov_b32_e32 v110, v133
	v_mov_b32_e32 v101, v133
	v_mov_b32_e32 v100, v133
	v_mov_b32_e32 v99, v133
	v_mov_b32_e32 v98, v133
	v_mov_b32_e32 v97, v133
	v_mov_b32_e32 v96, v133
	v_mov_b32_e32 v95, v133
	v_mov_b32_e32 v94, v133
	v_mov_b32_e32 v85, v133
	v_mov_b32_e32 v84, v133
	v_mov_b32_e32 v83, v133
	v_mov_b32_e32 v82, v133
	v_mov_b32_e32 v81, v133
	v_mov_b32_e32 v80, v133
	v_mov_b32_e32 v79, v133
	v_mov_b32_e32 v78, v133
	v_mov_b32_e32 v125, v133
	v_mov_b32_e32 v124, v133
	v_mov_b32_e32 v123, v133
	v_mov_b32_e32 v122, v133
	v_mov_b32_e32 v121, v133
	v_mov_b32_e32 v120, v133
	v_mov_b32_e32 v119, v133
	v_mov_b32_e32 v118, v133
	v_mov_b32_e32 v109, v133
	v_mov_b32_e32 v108, v133
	v_mov_b32_e32 v107, v133
	v_mov_b32_e32 v106, v133
	v_mov_b32_e32 v105, v133
	v_mov_b32_e32 v104, v133
	v_mov_b32_e32 v103, v133
	v_mov_b32_e32 v102, v133
	v_mov_b32_e32 v93, v133
	v_mov_b32_e32 v92, v133
	v_mov_b32_e32 v91, v133
	v_mov_b32_e32 v90, v133
	v_mov_b32_e32 v89, v133
	v_mov_b32_e32 v88, v133
	v_mov_b32_e32 v87, v133
	v_mov_b32_e32 v86, v133
	v_mov_b32_e32 v77, v133
	v_mov_b32_e32 v76, v133
	v_mov_b32_e32 v75, v133
	v_mov_b32_e32 v74, v133
	v_mov_b32_e32 v73, v133
	v_mov_b32_e32 v72, v133
	v_mov_b32_e32 v71, v133
	v_mov_b32_e32 v70, v133
	v_mov_b32_e32 v69, v133
	v_mov_b32_e32 v68, v133
	v_mov_b32_e32 v67, v133
	v_mov_b32_e32 v66, v133
	v_mov_b32_e32 v65, v133
	v_mov_b32_e32 v64, v133
	v_mov_b32_e32 v63, v133
	v_mov_b32_e32 v62, v133
	v_mov_b32_e32 v53, v133
	v_mov_b32_e32 v52, v133
	v_mov_b32_e32 v51, v133
	v_mov_b32_e32 v50, v133
	v_mov_b32_e32 v49, v133
	v_mov_b32_e32 v48, v133
	v_mov_b32_e32 v47, v133
	v_mov_b32_e32 v46, v133
	v_mov_b32_e32 v37, v133
	v_mov_b32_e32 v36, v133
	v_mov_b32_e32 v35, v133
	v_mov_b32_e32 v34, v133
	v_mov_b32_e32 v33, v133
	v_mov_b32_e32 v32, v133
	v_mov_b32_e32 v31, v133
	v_mov_b32_e32 v30, v133
	v_mov_b32_e32 v21, v133
	v_mov_b32_e32 v20, v133
	v_mov_b32_e32 v19, v133
	v_mov_b32_e32 v18, v133
	v_mov_b32_e32 v17, v133
	v_mov_b32_e32 v16, v133
	v_mov_b32_e32 v15, v133
	v_mov_b32_e32 v14, v133
	v_mov_b32_e32 v61, v133
	v_mov_b32_e32 v60, v133
	v_mov_b32_e32 v59, v133
	v_mov_b32_e32 v58, v133
	v_mov_b32_e32 v57, v133
	v_mov_b32_e32 v56, v133
	v_mov_b32_e32 v55, v133
	v_mov_b32_e32 v54, v133
	v_mov_b32_e32 v45, v133
	v_mov_b32_e32 v44, v133
	v_mov_b32_e32 v43, v133
	v_mov_b32_e32 v42, v133
	v_mov_b32_e32 v41, v133
	v_mov_b32_e32 v40, v133
	v_mov_b32_e32 v39, v133
	v_mov_b32_e32 v38, v133
	v_mov_b32_e32 v29, v133
	v_mov_b32_e32 v28, v133
	v_mov_b32_e32 v27, v133
	v_mov_b32_e32 v26, v133
	v_mov_b32_e32 v25, v133
	v_mov_b32_e32 v24, v133
	v_mov_b32_e32 v23, v133
	v_mov_b32_e32 v22, v133
	v_mov_b32_e32 v13, v133
	v_mov_b32_e32 v12, v133
	v_mov_b32_e32 v11, v133
	v_mov_b32_e32 v10, v133
	v_mov_b32_e32 v9, v133
	v_mov_b32_e32 v8, v133
	s_waitcnt lgkmcnt(0)
	v_mov_b32_e32 v7, v133
	v_mov_b32_e32 v6, v133
	s_cbranch_vccnz .LBB0_1193
	v_mov_b32_e32 v6, 0
	v_lshl_add_u64 v[134:135], v[134:135], 0, s[26:27]
	v_lshl_add_u64 v[136:137], v[136:137], 0, s[20:21]
	s_mov_b32 s10, 0
	v_mov_b32_e32 v7, v6
	v_mov_b32_e32 v8, v6
	v_mov_b32_e32 v9, v6
	v_mov_b32_e32 v10, v6
	v_mov_b32_e32 v11, v6
	v_mov_b32_e32 v12, v6
	v_mov_b32_e32 v13, v6
	v_mov_b32_e32 v22, v6
	v_mov_b32_e32 v23, v6
	v_mov_b32_e32 v24, v6
	v_mov_b32_e32 v25, v6
	v_mov_b32_e32 v26, v6
	v_mov_b32_e32 v27, v6
	v_mov_b32_e32 v28, v6
	v_mov_b32_e32 v29, v6
	v_mov_b32_e32 v38, v6
	v_mov_b32_e32 v39, v6
	v_mov_b32_e32 v40, v6
	v_mov_b32_e32 v41, v6
	v_mov_b32_e32 v42, v6
	v_mov_b32_e32 v43, v6
	v_mov_b32_e32 v44, v6
	v_mov_b32_e32 v45, v6
	v_mov_b32_e32 v54, v6
	v_mov_b32_e32 v55, v6
	v_mov_b32_e32 v56, v6
	v_mov_b32_e32 v57, v6
	v_mov_b32_e32 v58, v6
	v_mov_b32_e32 v59, v6
	v_mov_b32_e32 v60, v6
	v_mov_b32_e32 v61, v6
	v_mov_b32_e32 v14, v6
	v_mov_b32_e32 v15, v6
	v_mov_b32_e32 v16, v6
	v_mov_b32_e32 v17, v6
	v_mov_b32_e32 v18, v6
	v_mov_b32_e32 v19, v6
	v_mov_b32_e32 v20, v6
	v_mov_b32_e32 v21, v6
	v_mov_b32_e32 v30, v6
	v_mov_b32_e32 v31, v6
	v_mov_b32_e32 v32, v6
	v_mov_b32_e32 v33, v6
	v_mov_b32_e32 v34, v6
	v_mov_b32_e32 v35, v6
	v_mov_b32_e32 v36, v6
	v_mov_b32_e32 v37, v6
	v_mov_b32_e32 v46, v6
	v_mov_b32_e32 v47, v6
	v_mov_b32_e32 v48, v6
	v_mov_b32_e32 v49, v6
	v_mov_b32_e32 v50, v6
	v_mov_b32_e32 v51, v6
	v_mov_b32_e32 v52, v6
	v_mov_b32_e32 v53, v6
	v_mov_b32_e32 v62, v6
	v_mov_b32_e32 v63, v6
	v_mov_b32_e32 v64, v6
	v_mov_b32_e32 v65, v6
	v_mov_b32_e32 v66, v6
	v_mov_b32_e32 v67, v6
	v_mov_b32_e32 v68, v6
	v_mov_b32_e32 v69, v6
	v_mov_b32_e32 v70, v6
	v_mov_b32_e32 v71, v6
	v_mov_b32_e32 v72, v6
	v_mov_b32_e32 v73, v6
	v_mov_b32_e32 v74, v6
	v_mov_b32_e32 v75, v6
	v_mov_b32_e32 v76, v6
	v_mov_b32_e32 v77, v6
	v_mov_b32_e32 v86, v6
	v_mov_b32_e32 v87, v6
	v_mov_b32_e32 v88, v6
	v_mov_b32_e32 v89, v6
	v_mov_b32_e32 v90, v6
	v_mov_b32_e32 v91, v6
	v_mov_b32_e32 v92, v6
	v_mov_b32_e32 v93, v6
	v_mov_b32_e32 v102, v6
	v_mov_b32_e32 v103, v6
	v_mov_b32_e32 v104, v6
	v_mov_b32_e32 v105, v6
	v_mov_b32_e32 v106, v6
	v_mov_b32_e32 v107, v6
	v_mov_b32_e32 v108, v6
	v_mov_b32_e32 v109, v6
	v_mov_b32_e32 v118, v6
	v_mov_b32_e32 v119, v6
	v_mov_b32_e32 v120, v6
	v_mov_b32_e32 v121, v6
	v_mov_b32_e32 v122, v6
	v_mov_b32_e32 v123, v6
	v_mov_b32_e32 v124, v6
	v_mov_b32_e32 v125, v6
	v_mov_b32_e32 v78, v6
	v_mov_b32_e32 v79, v6
	v_mov_b32_e32 v80, v6
	v_mov_b32_e32 v81, v6
	v_mov_b32_e32 v82, v6
	v_mov_b32_e32 v83, v6
	v_mov_b32_e32 v84, v6
	v_mov_b32_e32 v85, v6
	v_mov_b32_e32 v94, v6
	v_mov_b32_e32 v95, v6
	v_mov_b32_e32 v96, v6
	v_mov_b32_e32 v97, v6
	v_mov_b32_e32 v98, v6
	v_mov_b32_e32 v99, v6
	v_mov_b32_e32 v100, v6
	v_mov_b32_e32 v101, v6
	v_mov_b32_e32 v110, v6
	v_mov_b32_e32 v111, v6
	v_mov_b32_e32 v112, v6
	v_mov_b32_e32 v113, v6
	v_mov_b32_e32 v114, v6
	v_mov_b32_e32 v115, v6
	v_mov_b32_e32 v116, v6
	v_mov_b32_e32 v117, v6
	v_mov_b32_e32 v126, v6
	v_mov_b32_e32 v127, v6
	v_mov_b32_e32 v128, v6
	v_mov_b32_e32 v129, v6
	v_mov_b32_e32 v130, v6
	v_mov_b32_e32 v131, v6
	v_mov_b32_e32 v132, v6
	v_mov_b32_e32 v133, v6
	.p2align	6

; template <class Epi, class Sched, bool ALIGN_EPI = false, bool SP2 = false>
; __device__ __forceinline__ void gemm_phase(PG8_LAS unsigned char* lds, const Gemm g, const Sched& S, const Epi& E) {
;     ...
;     f32x4 acc[2][2][4][2];
; #pragma unroll
;     for (int a = 0; a < 2; ++a)
; #pragma unroll
;         for (int b = 0; b < 2; ++b)
; #pragma unroll
;             for (int m = 0; m < 4; ++m)
; #pragma unroll
;                 for (int n = 0; n < 2; ++n) acc[a][b][m][n] = (f32x4){0.f, 0.f, 0.f, 0.f};
;     ...
;         if (!has_next) break;
; #pragma unroll
;         for (int a = 0; a < 2; ++a)
; #pragma unroll
;             for (int b = 0; b < 2; ++b)
; #pragma unroll
;                 for (int m = 0; m < 4; ++m)
; #pragma unroll
;                     for (int n = 0; n < 2; ++n) acc[a][b][m][n] = (f32x4){0.f, 0.f, 0.f, 0.f};
;         cur = nxt; cA = nA; cB = nB; ++ui;
.LBB0_1421:
	v_mov_b32_e32 v127, 0
	s_andn2_b64 vcc, exec, s[28:29]
	v_mov_b32_e32 v126, v127
	v_mov_b32_e32 v125, v127
	v_mov_b32_e32 v124, v127
	v_mov_b32_e32 v123, v127
	v_mov_b32_e32 v122, v127
	v_mov_b32_e32 v121, v127
	v_mov_b32_e32 v120, v127
	v_mov_b32_e32 v111, v127
	v_mov_b32_e32 v110, v127
	v_mov_b32_e32 v109, v127
	v_mov_b32_e32 v108, v127
	v_mov_b32_e32 v107, v127
	v_mov_b32_e32 v106, v127
	v_mov_b32_e32 v105, v127
	v_mov_b32_e32 v104, v127
	v_mov_b32_e32 v95, v127
	v_mov_b32_e32 v94, v127
	v_mov_b32_e32 v93, v127
	v_mov_b32_e32 v92, v127
	v_mov_b32_e32 v91, v127
	v_mov_b32_e32 v90, v127
	v_mov_b32_e32 v89, v127
	v_mov_b32_e32 v88, v127
	v_mov_b32_e32 v79, v127
	v_mov_b32_e32 v78, v127
	v_mov_b32_e32 v77, v127
	v_mov_b32_e32 v76, v127
	v_mov_b32_e32 v75, v127
	v_mov_b32_e32 v74, v127
	v_mov_b32_e32 v73, v127
	v_mov_b32_e32 v72, v127
	v_mov_b32_e32 v119, v127
	v_mov_b32_e32 v118, v127
	v_mov_b32_e32 v117, v127
	v_mov_b32_e32 v116, v127
	v_mov_b32_e32 v115, v127
	v_mov_b32_e32 v114, v127
	v_mov_b32_e32 v113, v127
	v_mov_b32_e32 v112, v127
	v_mov_b32_e32 v103, v127
	v_mov_b32_e32 v102, v127
	v_mov_b32_e32 v101, v127
	v_mov_b32_e32 v100, v127
	v_mov_b32_e32 v99, v127
	v_mov_b32_e32 v98, v127
	v_mov_b32_e32 v97, v127
	v_mov_b32_e32 v96, v127
	v_mov_b32_e32 v87, v127
	v_mov_b32_e32 v86, v127
	v_mov_b32_e32 v85, v127
	v_mov_b32_e32 v84, v127
	v_mov_b32_e32 v83, v127
	v_mov_b32_e32 v82, v127
	v_mov_b32_e32 v81, v127
	v_mov_b32_e32 v80, v127
	v_mov_b32_e32 v71, v127
	v_mov_b32_e32 v70, v127
	v_mov_b32_e32 v69, v127
	v_mov_b32_e32 v68, v127
	v_mov_b32_e32 v67, v127
	v_mov_b32_e32 v66, v127
	v_mov_b32_e32 v65, v127
	v_mov_b32_e32 v64, v127
	v_mov_b32_e32 v63, v127
	v_mov_b32_e32 v62, v127
	v_mov_b32_e32 v61, v127
	v_mov_b32_e32 v60, v127
	v_mov_b32_e32 v59, v127
	v_mov_b32_e32 v58, v127
	v_mov_b32_e32 v57, v127
	v_mov_b32_e32 v56, v127
	v_mov_b32_e32 v47, v127
	v_mov_b32_e32 v46, v127
	v_mov_b32_e32 v45, v127
	v_mov_b32_e32 v44, v127
	v_mov_b32_e32 v43, v127
	v_mov_b32_e32 v42, v127
	v_mov_b32_e32 v41, v127
	v_mov_b32_e32 v40, v127
	v_mov_b32_e32 v31, v127
	v_mov_b32_e32 v30, v127
	v_mov_b32_e32 v29, v127
	v_mov_b32_e32 v28, v127
	v_mov_b32_e32 v27, v127
	v_mov_b32_e32 v26, v127
	v_mov_b32_e32 v25, v127
	v_mov_b32_e32 v24, v127
	v_mov_b32_e32 v15, v127
	v_mov_b32_e32 v14, v127
	v_mov_b32_e32 v13, v127
	v_mov_b32_e32 v12, v127
	v_mov_b32_e32 v11, v127
	v_mov_b32_e32 v10, v127
	v_mov_b32_e32 v9, v127
	v_mov_b32_e32 v8, v127
	v_mov_b32_e32 v55, v127
	v_mov_b32_e32 v54, v127
	v_mov_b32_e32 v53, v127
	v_mov_b32_e32 v52, v127
	v_mov_b32_e32 v51, v127
	v_mov_b32_e32 v50, v127
	v_mov_b32_e32 v49, v127
	v_mov_b32_e32 v48, v127
	v_mov_b32_e32 v39, v127
	v_mov_b32_e32 v38, v127
	v_mov_b32_e32 v37, v127
	v_mov_b32_e32 v36, v127
	v_mov_b32_e32 v35, v127
	v_mov_b32_e32 v34, v127
	v_mov_b32_e32 v33, v127
	v_mov_b32_e32 v32, v127
	v_mov_b32_e32 v23, v127
	v_mov_b32_e32 v22, v127
	v_mov_b32_e32 v21, v127
	v_mov_b32_e32 v20, v127
	v_mov_b32_e32 v19, v127
	v_mov_b32_e32 v18, v127
	v_mov_b32_e32 v17, v127
	v_mov_b32_e32 v16, v127
	v_mov_b32_e32 v7, v127
	v_mov_b32_e32 v6, v127
	v_mov_b32_e32 v5, v127
	v_mov_b32_e32 v4, v127
	v_mov_b32_e32 v3, v127
	v_mov_b32_e32 v2, v127
	v_mov_b32_e32 v1, v127
	v_mov_b32_e32 v0, v127
	s_cbranch_vccnz .LBB0_1424
	v_mov_b32_e32 v0, 0
	v_lshl_add_u64 v[128:129], v[128:129], 0, s[36:37]
	v_lshl_add_u64 v[130:131], v[130:131], 0, s[26:27]
	s_mov_b32 s10, 0
	v_mov_b32_e32 v1, v0
	v_mov_b32_e32 v2, v0
	v_mov_b32_e32 v3, v0
	v_mov_b32_e32 v4, v0
	v_mov_b32_e32 v5, v0
	v_mov_b32_e32 v6, v0
	v_mov_b32_e32 v7, v0
	v_mov_b32_e32 v16, v0
	v_mov_b32_e32 v17, v0
	v_mov_b32_e32 v18, v0
	v_mov_b32_e32 v19, v0
	v_mov_b32_e32 v20, v0
	v_mov_b32_e32 v21, v0
	v_mov_b32_e32 v22, v0
	v_mov_b32_e32 v23, v0
	v_mov_b32_e32 v32, v0
	v_mov_b32_e32 v33, v0
	v_mov_b32_e32 v34, v0
	v_mov_b32_e32 v35, v0
	v_mov_b32_e32 v36, v0
	v_mov_b32_e32 v37, v0
	v_mov_b32_e32 v38, v0
	v_mov_b32_e32 v39, v0
	v_mov_b32_e32 v48, v0
	v_mov_b32_e32 v49, v0
	v_mov_b32_e32 v50, v0
	v_mov_b32_e32 v51, v0
	v_mov_b32_e32 v52, v0
	v_mov_b32_e32 v53, v0
	v_mov_b32_e32 v54, v0
	v_mov_b32_e32 v55, v0
	v_mov_b32_e32 v8, v0
	v_mov_b32_e32 v9, v0
	v_mov_b32_e32 v10, v0
	v_mov_b32_e32 v11, v0
	v_mov_b32_e32 v12, v0
	v_mov_b32_e32 v13, v0
	v_mov_b32_e32 v14, v0
	v_mov_b32_e32 v15, v0
	v_mov_b32_e32 v24, v0
	v_mov_b32_e32 v25, v0
	v_mov_b32_e32 v26, v0
	v_mov_b32_e32 v27, v0
	v_mov_b32_e32 v28, v0
	v_mov_b32_e32 v29, v0
	v_mov_b32_e32 v30, v0
	v_mov_b32_e32 v31, v0
	v_mov_b32_e32 v40, v0
	v_mov_b32_e32 v41, v0
	v_mov_b32_e32 v42, v0
	v_mov_b32_e32 v43, v0
	v_mov_b32_e32 v44, v0
	v_mov_b32_e32 v45, v0
	v_mov_b32_e32 v46, v0
	v_mov_b32_e32 v47, v0
	v_mov_b32_e32 v56, v0
	v_mov_b32_e32 v57, v0
	v_mov_b32_e32 v58, v0
	v_mov_b32_e32 v59, v0
	v_mov_b32_e32 v60, v0
	v_mov_b32_e32 v61, v0
	v_mov_b32_e32 v62, v0
	v_mov_b32_e32 v63, v0
	v_mov_b32_e32 v64, v0
	v_mov_b32_e32 v65, v0
	v_mov_b32_e32 v66, v0
	v_mov_b32_e32 v67, v0
	v_mov_b32_e32 v68, v0
	v_mov_b32_e32 v69, v0
	v_mov_b32_e32 v70, v0
	v_mov_b32_e32 v71, v0
	v_mov_b32_e32 v80, v0
	v_mov_b32_e32 v81, v0
	v_mov_b32_e32 v82, v0
	v_mov_b32_e32 v83, v0
	v_mov_b32_e32 v84, v0
	v_mov_b32_e32 v85, v0
	v_mov_b32_e32 v86, v0
	v_mov_b32_e32 v87, v0
	v_mov_b32_e32 v96, v0
	v_mov_b32_e32 v97, v0
	v_mov_b32_e32 v98, v0
	v_mov_b32_e32 v99, v0
	v_mov_b32_e32 v100, v0
	v_mov_b32_e32 v101, v0
	v_mov_b32_e32 v102, v0
	v_mov_b32_e32 v103, v0
	v_mov_b32_e32 v112, v0
	v_mov_b32_e32 v113, v0
	v_mov_b32_e32 v114, v0
	v_mov_b32_e32 v115, v0
	v_mov_b32_e32 v116, v0
	v_mov_b32_e32 v117, v0
	v_mov_b32_e32 v118, v0
	v_mov_b32_e32 v119, v0
	v_mov_b32_e32 v72, v0
	v_mov_b32_e32 v73, v0
	v_mov_b32_e32 v74, v0
	v_mov_b32_e32 v75, v0
	v_mov_b32_e32 v76, v0
	v_mov_b32_e32 v77, v0
	v_mov_b32_e32 v78, v0
	v_mov_b32_e32 v79, v0
	v_mov_b32_e32 v88, v0
	v_mov_b32_e32 v89, v0
	v_mov_b32_e32 v90, v0
	v_mov_b32_e32 v91, v0
	v_mov_b32_e32 v92, v0
	v_mov_b32_e32 v93, v0
	v_mov_b32_e32 v94, v0
	v_mov_b32_e32 v95, v0
	v_mov_b32_e32 v104, v0
	v_mov_b32_e32 v105, v0
	v_mov_b32_e32 v106, v0
	v_mov_b32_e32 v107, v0
	v_mov_b32_e32 v108, v0
	v_mov_b32_e32 v109, v0
	v_mov_b32_e32 v110, v0
	v_mov_b32_e32 v111, v0
	v_mov_b32_e32 v120, v0
	v_mov_b32_e32 v121, v0
	v_mov_b32_e32 v122, v0
	v_mov_b32_e32 v123, v0
	v_mov_b32_e32 v124, v0
	v_mov_b32_e32 v125, v0
	v_mov_b32_e32 v126, v0
	v_mov_b32_e32 v127, v0
	.p2align	6
; #define PG8_STAGE(bufoff, gbase, voff) do { _Pragma("unroll") for (int _i = 0; _i < 2; ++_i) \
;         __builtin_amdgcn_global_load_lds((const unsigned*)((const char*)(gbase) + (voff)[_i]), (PG8_LAS unsigned*)(lds + (bufoff) + ldsw + _i * 8192), 16, 0, 0); } while (0)
; #define PG8_LDA(dst, b, h) do { _Pragma("unroll") for (int m = 0; m < 4; ++m) _Pragma("unroll") for (int k = 0; k < 2; ++k) dst[m][k] = *(const PG8_LAS bf16x8*)(lds + PG8_SA(b, h) + aoff + m * 2048 + k * 1024); } while (0)
; #define PG8_LDB(dst, b, h) do { _Pragma("unroll") for (int n = 0; n < 2; ++n) _Pragma("unroll") for (int k = 0; k < 2; ++k) dst[n][k] = *(const PG8_LAS bf16x8*)(lds + PG8_SB(b, h) + boff + n * 2048 + k * 1024); } while (0)
; template <class Epi, class Sched, bool ALIGN_EPI = false, bool SP2 = false>
; __device__ __forceinline__ void gemm_phase(PG8_LAS unsigned char* lds, const Gemm g, const Sched& S, const Epi& E) {
;     ...
;         for (int t = 0; t < nt; t += 2) {
;             const bool last = (t == nt - 2);
;             const char* a1 = cA + (size_t)(t + 1) * kstep;
;             const char* a2 = last ? nA : cA + (size_t)(t + 2) * kstep; const char* b2 = last ? nB : cB + (size_t)(t + 2) * kstep;
;             const char* a3 = a2 + kstep; const char* b3 = b2 + kstep;
;             if (last && has_next) S.a_ready(nxt);
;             if constexpr (SP2) {
;             PG8_LDB(B0, 0, 0); PG8_LDB(B1, 0, 1); PG8_SCHED; PG8_LDA(At, 0, 0); PG8_STAGE(PG8_SA(1, 1), a1 + hstep, voffA);
;             PG8_WAIT_V(8); PG8_WAIT_L(0); PG8_BAR; PG8_MMA(0, 0, At, B0); PG8_MMA(0, 1, At, B1); PG8_BAR; PG8_SCHED;
;             PG8_LDA(At, 0, 1); PG8_STAGE(PG8_SB(0, 0), b2, voffB); PG8_STAGE(PG8_SB(0, 1), b2 + hstep, voffB); PG8_STAGE(PG8_SA(0, 0), a2, voffA);
;             PG8_WAIT_V(8); PG8_WAIT_L(0); PG8_BAR; PG8_MMA(1, 0, At, B0); PG8_MMA(1, 1, At, B1); PG8_BAR; PG8_SCHED;
;             PG8_LDB(B0, 1, 0); PG8_LDB(B1, 1, 1); PG8_SCHED; PG8_LDA(At, 1, 0); PG8_STAGE(PG8_SA(0, 1), a2 + hstep, voffA);
;             PG8_WAIT_V(8); PG8_WAIT_L(0); PG8_BAR; PG8_MMA(0, 0, At, B0); PG8_MMA(0, 1, At, B1); PG8_BAR; PG8_SCHED;
;             PG8_LDA(At, 1, 1); PG8_STAGE(PG8_SB(1, 0), b3, voffB); PG8_STAGE(PG8_SB(1, 1), b3 + hstep, voffB); PG8_STAGE(PG8_SA(1, 0), a3, voffA);
;             PG8_WAIT_V(8); PG8_WAIT_L(0); PG8_BAR; PG8_MMA(1, 0, At, B0); PG8_MMA(1, 1, At, B1); PG8_BAR; PG8_SCHED;
.LBB0_1423:
	v_add_u32_e32 v152, s81, v169
	v_add_u32_e32 v165, s82, v169
	ds_read_b128 v[132:135], v152
	ds_read_b128 v[136:139], v152 offset:1024
	ds_read_b128 v[174:177], v152 offset:2048
	ds_read_b128 v[178:181], v152 offset:3072
	ds_read_b128 v[182:185], v165
	ds_read_b128 v[186:189], v165 offset:1024
	ds_read_b128 v[190:193], v165 offset:2048
	ds_read_b128 v[194:197], v165 offset:3072
	s_cmp_eq_u32 s74, s10
	v_lshl_add_u64 v[198:199], v[130:131], 0, s[26:27]
	s_cselect_b64 vcc, -1, 0
	s_add_i32 s10, s10, 2
	v_cndmask_b32_e32 v211, v199, v171, vcc
	v_cndmask_b32_e32 v210, v198, v170, vcc
	v_cndmask_b32_e32 v215, v129, v173, vcc
	v_cndmask_b32_e32 v214, v128, v172, vcc
	v_lshl_add_u64 v[240:241], v[130:131], 0, v[160:161]
	s_add_i32 m0, s47, 0xc000
	ds_read_b128 v[198:201], v213
	ds_read_b128 v[202:205], v213 offset:1024
	ds_read_b128 v[206:209], v213 offset:2048
	ds_read_b128 v[220:223], v213 offset:3072
	ds_read_b128 v[224:227], v213 offset:4096
	ds_read_b128 v[228:231], v213 offset:5120
	ds_read_b128 v[232:235], v213 offset:6144
	ds_read_b128 v[236:239], v213 offset:7168
	global_load_lds_dwordx4 v[240:241], off
	v_lshl_add_u64 v[240:241], v[130:131], 0, v[158:159]
	s_add_i32 m0, s47, 0xe000
	s_nop 0
	global_load_lds_dwordx4 v[240:241], off
	s_waitcnt vmcnt(8)
	s_waitcnt lgkmcnt(0)
	s_setprio 1
	s_barrier
	v_mfma_f32_16x16x32_bf16 v[124:127], v[132:135], v[198:201], v[124:127]
	v_mfma_f32_16x16x32_bf16 v[120:123], v[174:177], v[198:201], v[120:123]
	v_mfma_f32_16x16x32_bf16 v[108:111], v[132:135], v[206:209], v[108:111]
	v_mfma_f32_16x16x32_bf16 v[104:107], v[174:177], v[206:209], v[104:107]
	v_mfma_f32_16x16x32_bf16 v[92:95], v[132:135], v[224:227], v[92:95]
	v_mfma_f32_16x16x32_bf16 v[88:91], v[174:177], v[224:227], v[88:91]
	v_mfma_f32_16x16x32_bf16 v[76:79], v[132:135], v[232:235], v[76:79]
	v_mfma_f32_16x16x32_bf16 v[72:75], v[174:177], v[232:235], v[72:75]
	v_mfma_f32_16x16x32_bf16 v[124:127], v[136:139], v[202:205], v[124:127]
	v_mfma_f32_16x16x32_bf16 v[120:123], v[178:181], v[202:205], v[120:123]
	v_mfma_f32_16x16x32_bf16 v[108:111], v[136:139], v[220:223], v[108:111]
	v_mfma_f32_16x16x32_bf16 v[104:107], v[178:181], v[220:223], v[104:107]
	v_mfma_f32_16x16x32_bf16 v[92:95], v[136:139], v[228:231], v[92:95]
	v_mfma_f32_16x16x32_bf16 v[88:91], v[178:181], v[228:231], v[88:91]
	v_mfma_f32_16x16x32_bf16 v[76:79], v[136:139], v[236:239], v[76:79]
	v_mfma_f32_16x16x32_bf16 v[72:75], v[178:181], v[236:239], v[72:75]
	s_cmp_eq_u32 s22, 12
	s_cbranch_scc1 .Lio_skipk0
	v_mfma_f32_16x16x32_bf16 v[116:119], v[182:185], v[198:201], v[116:119]
	v_mfma_f32_16x16x32_bf16 v[112:115], v[190:193], v[198:201], v[112:115]
	v_mfma_f32_16x16x32_bf16 v[100:103], v[182:185], v[206:209], v[100:103]
	v_mfma_f32_16x16x32_bf16 v[96:99], v[190:193], v[206:209], v[96:99]
	v_mfma_f32_16x16x32_bf16 v[84:87], v[182:185], v[224:227], v[84:87]
	v_mfma_f32_16x16x32_bf16 v[80:83], v[190:193], v[224:227], v[80:83]
	v_mfma_f32_16x16x32_bf16 v[68:71], v[182:185], v[232:235], v[68:71]
	v_mfma_f32_16x16x32_bf16 v[64:67], v[190:193], v[232:235], v[64:67]
	v_mfma_f32_16x16x32_bf16 v[116:119], v[186:189], v[202:205], v[116:119]
	v_mfma_f32_16x16x32_bf16 v[112:115], v[194:197], v[202:205], v[112:115]
	v_mfma_f32_16x16x32_bf16 v[100:103], v[186:189], v[220:223], v[100:103]
	v_mfma_f32_16x16x32_bf16 v[96:99], v[194:197], v[220:223], v[96:99]
	v_mfma_f32_16x16x32_bf16 v[84:87], v[186:189], v[228:231], v[84:87]
	v_mfma_f32_16x16x32_bf16 v[80:83], v[194:197], v[228:231], v[80:83]
	v_mfma_f32_16x16x32_bf16 v[68:71], v[186:189], v[236:239], v[68:71]
	v_mfma_f32_16x16x32_bf16 v[64:67], v[194:197], v[236:239], v[64:67]
.Lio_skipk0:
	s_setprio 0
	s_barrier
	s_add_i32 s11, s81, s41
	v_lshl_add_u64 v[240:241], v[214:215], 0, v[146:147]
	s_mov_b32 m0, s11
	ds_read_b128 v[198:201], v213 offset:16384
	ds_read_b128 v[202:205], v213 offset:17408
	ds_read_b128 v[206:209], v213 offset:18432
	ds_read_b128 v[220:223], v213 offset:19456
	ds_read_b128 v[224:227], v213 offset:20480
	ds_read_b128 v[228:231], v213 offset:21504
	ds_read_b128 v[232:235], v213 offset:22528
	ds_read_b128 v[236:239], v213 offset:23552
	global_load_lds_dwordx4 v[240:241], off
	v_lshl_add_u64 v[242:243], v[214:215], 0, v[150:151]
	s_add_i32 m0, s11, 0x2000
	v_lshl_add_u64 v[214:215], v[214:215], 0, s[18:19]
	s_add_i32 s11, s82, s41
	global_load_lds_dwordx4 v[242:243], off
	v_lshl_add_u64 v[244:245], v[214:215], 0, v[146:147]
	s_mov_b32 m0, s11
	v_lshl_add_u64 v[214:215], v[214:215], 0, v[150:151]
	global_load_lds_dwordx4 v[244:245], off
	s_add_i32 m0, s11, 0x2000
	v_lshl_add_u64 v[246:247], v[210:211], 0, v[144:145]
	global_load_lds_dwordx4 v[214:215], off
	s_mov_b32 m0, s47
	v_lshl_add_u64 v[248:249], v[210:211], 0, v[148:149]
	global_load_lds_dwordx4 v[246:247], off
	s_mov_b32 m0, s55
	s_nop 0
	global_load_lds_dwordx4 v[248:249], off
	s_waitcnt vmcnt(8)
	s_waitcnt lgkmcnt(0)
	s_setprio 1
	s_barrier
	v_mfma_f32_16x16x32_bf16 v[60:63], v[132:135], v[198:201], v[60:63]
	v_mfma_f32_16x16x32_bf16 v[56:59], v[174:177], v[198:201], v[56:59]
	v_mfma_f32_16x16x32_bf16 v[44:47], v[132:135], v[206:209], v[44:47]
	v_mfma_f32_16x16x32_bf16 v[40:43], v[174:177], v[206:209], v[40:43]
	v_mfma_f32_16x16x32_bf16 v[28:31], v[132:135], v[224:227], v[28:31]
	v_mfma_f32_16x16x32_bf16 v[24:27], v[174:177], v[224:227], v[24:27]
	v_mfma_f32_16x16x32_bf16 v[12:15], v[132:135], v[232:235], v[12:15]
	v_mfma_f32_16x16x32_bf16 v[8:11], v[174:177], v[232:235], v[8:11]
	v_mfma_f32_16x16x32_bf16 v[60:63], v[136:139], v[202:205], v[60:63]
	v_mfma_f32_16x16x32_bf16 v[56:59], v[178:181], v[202:205], v[56:59]
	v_mfma_f32_16x16x32_bf16 v[44:47], v[136:139], v[220:223], v[44:47]
	v_mfma_f32_16x16x32_bf16 v[40:43], v[178:181], v[220:223], v[40:43]
	v_mfma_f32_16x16x32_bf16 v[28:31], v[136:139], v[228:231], v[28:31]
	v_mfma_f32_16x16x32_bf16 v[24:27], v[178:181], v[228:231], v[24:27]
	v_mfma_f32_16x16x32_bf16 v[12:15], v[136:139], v[236:239], v[12:15]
	v_mfma_f32_16x16x32_bf16 v[8:11], v[178:181], v[236:239], v[8:11]
	s_cmp_eq_u32 s22, 12
	s_cbranch_scc1 .Lio_skipk1
; #define PG8_STAGE(bufoff, gbase, voff) do { _Pragma("unroll") for (int _i = 0; _i < 2; ++_i) \
;         __builtin_amdgcn_global_load_lds((const unsigned*)((const char*)(gbase) + (voff)[_i]), (PG8_LAS unsigned*)(lds + (bufoff) + ldsw + _i * 8192), 16, 0, 0); } while (0)
; #define PG8_LDA(dst, b, h) do { _Pragma("unroll") for (int m = 0; m < 4; ++m) _Pragma("unroll") for (int k = 0; k < 2; ++k) dst[m][k] = *(const PG8_LAS bf16x8*)(lds + PG8_SA(b, h) + aoff + m * 2048 + k * 1024); } while (0)
; #define PG8_LDB(dst, b, h) do { _Pragma("unroll") for (int n = 0; n < 2; ++n) _Pragma("unroll") for (int k = 0; k < 2; ++k) dst[n][k] = *(const PG8_LAS bf16x8*)(lds + PG8_SB(b, h) + boff + n * 2048 + k * 1024); } while (0)
; template <class Epi, class Sched, bool ALIGN_EPI = false, bool SP2 = false>
; __device__ __forceinline__ void gemm_phase(PG8_LAS unsigned char* lds, const Gemm g, const Sched& S, const Epi& E) {
;     ...
;         for (int t = 0; t < nt; t += 2) {
;             const bool last = (t == nt - 2);
;             const char* a1 = cA + (size_t)(t + 1) * kstep;
;             const char* a2 = last ? nA : cA + (size_t)(t + 2) * kstep; const char* b2 = last ? nB : cB + (size_t)(t + 2) * kstep;
;             const char* a3 = a2 + kstep; const char* b3 = b2 + kstep;
;             if (last && has_next) S.a_ready(nxt);
;             if constexpr (SP2) {
;             PG8_LDB(B0, 0, 0); PG8_LDB(B1, 0, 1); PG8_SCHED; PG8_LDA(At, 0, 0); PG8_STAGE(PG8_SA(1, 1), a1 + hstep, voffA);
;             PG8_WAIT_V(8); PG8_WAIT_L(0); PG8_BAR; PG8_MMA(0, 0, At, B0); PG8_MMA(0, 1, At, B1); PG8_BAR; PG8_SCHED;
;             PG8_LDA(At, 0, 1); PG8_STAGE(PG8_SB(0, 0), b2, voffB); PG8_STAGE(PG8_SB(0, 1), b2 + hstep, voffB); PG8_STAGE(PG8_SA(0, 0), a2, voffA);
;             PG8_WAIT_V(8); PG8_WAIT_L(0); PG8_BAR; PG8_MMA(1, 0, At, B0); PG8_MMA(1, 1, At, B1); PG8_BAR; PG8_SCHED;
;             PG8_LDB(B0, 1, 0); PG8_LDB(B1, 1, 1); PG8_SCHED; PG8_LDA(At, 1, 0); PG8_STAGE(PG8_SA(0, 1), a2 + hstep, voffA);
;             PG8_WAIT_V(8); PG8_WAIT_L(0); PG8_BAR; PG8_MMA(0, 0, At, B0); PG8_MMA(0, 1, At, B1); PG8_BAR; PG8_SCHED;
;             PG8_LDA(At, 1, 1); PG8_STAGE(PG8_SB(1, 0), b3, voffB); PG8_STAGE(PG8_SB(1, 1), b3 + hstep, voffB); PG8_STAGE(PG8_SA(1, 0), a3, voffA);
;             PG8_WAIT_V(8); PG8_WAIT_L(0); PG8_BAR; PG8_MMA(1, 0, At, B0); PG8_MMA(1, 1, At, B1); PG8_BAR; PG8_SCHED;
	v_mfma_f32_16x16x32_bf16 v[52:55], v[182:185], v[198:201], v[52:55]
	v_mfma_f32_16x16x32_bf16 v[48:51], v[190:193], v[198:201], v[48:51]
	v_mfma_f32_16x16x32_bf16 v[36:39], v[182:185], v[206:209], v[36:39]
	v_mfma_f32_16x16x32_bf16 v[32:35], v[190:193], v[206:209], v[32:35]
	v_mfma_f32_16x16x32_bf16 v[20:23], v[182:185], v[224:227], v[20:23]
	v_mfma_f32_16x16x32_bf16 v[16:19], v[190:193], v[224:227], v[16:19]
	v_mfma_f32_16x16x32_bf16 v[4:7], v[182:185], v[232:235], v[4:7]
	v_mfma_f32_16x16x32_bf16 v[0:3], v[190:193], v[232:235], v[0:3]
	v_mfma_f32_16x16x32_bf16 v[52:55], v[186:189], v[202:205], v[52:55]
	v_mfma_f32_16x16x32_bf16 v[48:51], v[194:197], v[202:205], v[48:51]
	v_mfma_f32_16x16x32_bf16 v[36:39], v[186:189], v[220:223], v[36:39]
	v_mfma_f32_16x16x32_bf16 v[32:35], v[194:197], v[220:223], v[32:35]
	v_mfma_f32_16x16x32_bf16 v[20:23], v[186:189], v[228:231], v[20:23]
	v_mfma_f32_16x16x32_bf16 v[16:19], v[194:197], v[228:231], v[16:19]
	v_mfma_f32_16x16x32_bf16 v[4:7], v[186:189], v[236:239], v[4:7]
	v_mfma_f32_16x16x32_bf16 v[0:3], v[194:197], v[236:239], v[0:3]
.Lio_skipk1:
	s_setprio 0
	s_barrier
	s_add_i32 s11, 0, 0x18000
	v_add_u32_e32 v152, s11, v169
	s_add_i32 s13, 0, 0x1c000
	ds_read_b128 v[132:135], v152
	ds_read_b128 v[136:139], v152 offset:1024
	ds_read_b128 v[174:177], v152 offset:2048
	ds_read_b128 v[178:181], v152 offset:3072
	v_add_u32_e32 v152, s13, v169
	ds_read_b128 v[182:185], v152
	ds_read_b128 v[186:189], v152 offset:1024
	ds_read_b128 v[190:193], v152 offset:2048
	ds_read_b128 v[194:197], v152 offset:3072
	v_lshl_add_u64 v[210:211], v[210:211], 0, s[18:19]
	s_mov_b32 m0, s57
	v_lshl_add_u64 v[250:251], v[210:211], 0, v[144:145]
	ds_read_b128 v[198:201], v213 offset:32768
	ds_read_b128 v[202:205], v213 offset:33792
	ds_read_b128 v[206:209], v213 offset:34816
	ds_read_b128 v[220:223], v213 offset:35840
	ds_read_b128 v[224:227], v213 offset:36864
	ds_read_b128 v[228:231], v213 offset:37888
	ds_read_b128 v[232:235], v213 offset:38912
	ds_read_b128 v[236:239], v213 offset:39936
	global_load_lds_dwordx4 v[250:251], off
	v_lshl_add_u64 v[210:211], v[210:211], 0, v[148:149]
	s_mov_b32 m0, s59
	s_nop 0
	global_load_lds_dwordx4 v[210:211], off
	s_waitcnt vmcnt(8)
	s_waitcnt lgkmcnt(0)
	s_setprio 1
	s_barrier
	v_mfma_f32_16x16x32_bf16 v[124:127], v[132:135], v[198:201], v[124:127]
	v_mfma_f32_16x16x32_bf16 v[120:123], v[174:177], v[198:201], v[120:123]
	v_mfma_f32_16x16x32_bf16 v[108:111], v[132:135], v[206:209], v[108:111]
	v_mfma_f32_16x16x32_bf16 v[104:107], v[174:177], v[206:209], v[104:107]
	v_mfma_f32_16x16x32_bf16 v[92:95], v[132:135], v[224:227], v[92:95]
	v_mfma_f32_16x16x32_bf16 v[88:91], v[174:177], v[224:227], v[88:91]
	v_mfma_f32_16x16x32_bf16 v[76:79], v[132:135], v[232:235], v[76:79]
	v_mfma_f32_16x16x32_bf16 v[72:75], v[174:177], v[232:235], v[72:75]
	v_mfma_f32_16x16x32_bf16 v[124:127], v[136:139], v[202:205], v[124:127]
	v_mfma_f32_16x16x32_bf16 v[120:123], v[178:181], v[202:205], v[120:123]
	v_mfma_f32_16x16x32_bf16 v[108:111], v[136:139], v[220:223], v[108:111]
	v_mfma_f32_16x16x32_bf16 v[104:107], v[178:181], v[220:223], v[104:107]
	v_mfma_f32_16x16x32_bf16 v[92:95], v[136:139], v[228:231], v[92:95]
	v_mfma_f32_16x16x32_bf16 v[88:91], v[178:181], v[228:231], v[88:91]
	v_mfma_f32_16x16x32_bf16 v[76:79], v[136:139], v[236:239], v[76:79]
	v_mfma_f32_16x16x32_bf16 v[72:75], v[178:181], v[236:239], v[72:75]
	s_cmp_eq_u32 s22, 12
	s_cbranch_scc1 .Lio_skipk2
	v_mfma_f32_16x16x32_bf16 v[116:119], v[182:185], v[198:201], v[116:119]
	v_mfma_f32_16x16x32_bf16 v[112:115], v[190:193], v[198:201], v[112:115]
	v_mfma_f32_16x16x32_bf16 v[100:103], v[182:185], v[206:209], v[100:103]
	v_mfma_f32_16x16x32_bf16 v[96:99], v[190:193], v[206:209], v[96:99]
	v_mfma_f32_16x16x32_bf16 v[84:87], v[182:185], v[224:227], v[84:87]
	v_mfma_f32_16x16x32_bf16 v[80:83], v[190:193], v[224:227], v[80:83]
	v_mfma_f32_16x16x32_bf16 v[68:71], v[182:185], v[232:235], v[68:71]
	v_mfma_f32_16x16x32_bf16 v[64:67], v[190:193], v[232:235], v[64:67]
	v_mfma_f32_16x16x32_bf16 v[116:119], v[186:189], v[202:205], v[116:119]
	v_mfma_f32_16x16x32_bf16 v[112:115], v[194:197], v[202:205], v[112:115]
	v_mfma_f32_16x16x32_bf16 v[100:103], v[186:189], v[220:223], v[100:103]
	v_mfma_f32_16x16x32_bf16 v[96:99], v[194:197], v[220:223], v[96:99]
	v_mfma_f32_16x16x32_bf16 v[84:87], v[186:189], v[228:231], v[84:87]
	v_mfma_f32_16x16x32_bf16 v[80:83], v[194:197], v[228:231], v[80:83]
	v_mfma_f32_16x16x32_bf16 v[68:71], v[186:189], v[236:239], v[68:71]
	v_mfma_f32_16x16x32_bf16 v[64:67], v[194:197], v[236:239], v[64:67]
; #define PG8_STAGE(bufoff, gbase, voff) do { _Pragma("unroll") for (int _i = 0; _i < 2; ++_i) \
;         __builtin_amdgcn_global_load_lds((const unsigned*)((const char*)(gbase) + (voff)[_i]), (PG8_LAS unsigned*)(lds + (bufoff) + ldsw + _i * 8192), 16, 0, 0); } while (0)
; #define PG8_LDA(dst, b, h) do { _Pragma("unroll") for (int m = 0; m < 4; ++m) _Pragma("unroll") for (int k = 0; k < 2; ++k) dst[m][k] = *(const PG8_LAS bf16x8*)(lds + PG8_SA(b, h) + aoff + m * 2048 + k * 1024); } while (0)
; #define PG8_LDB(dst, b, h) do { _Pragma("unroll") for (int n = 0; n < 2; ++n) _Pragma("unroll") for (int k = 0; k < 2; ++k) dst[n][k] = *(const PG8_LAS bf16x8*)(lds + PG8_SB(b, h) + boff + n * 2048 + k * 1024); } while (0)
; template <class Epi, class Sched, bool ALIGN_EPI = false, bool SP2 = false>
; __device__ __forceinline__ void gemm_phase(PG8_LAS unsigned char* lds, const Gemm g, const Sched& S, const Epi& E) {
;     ...
;         for (int t = 0; t < nt; t += 2) {
;             const bool last = (t == nt - 2);
;             const char* a1 = cA + (size_t)(t + 1) * kstep;
;             const char* a2 = last ? nA : cA + (size_t)(t + 2) * kstep; const char* b2 = last ? nB : cB + (size_t)(t + 2) * kstep;
;             const char* a3 = a2 + kstep; const char* b3 = b2 + kstep;
;             if (last && has_next) S.a_ready(nxt);
;             if constexpr (SP2) {
;             PG8_LDB(B0, 0, 0); PG8_LDB(B1, 0, 1); PG8_SCHED; PG8_LDA(At, 0, 0); PG8_STAGE(PG8_SA(1, 1), a1 + hstep, voffA);
;             PG8_WAIT_V(8); PG8_WAIT_L(0); PG8_BAR; PG8_MMA(0, 0, At, B0); PG8_MMA(0, 1, At, B1); PG8_BAR; PG8_SCHED;
;             PG8_LDA(At, 0, 1); PG8_STAGE(PG8_SB(0, 0), b2, voffB); PG8_STAGE(PG8_SB(0, 1), b2 + hstep, voffB); PG8_STAGE(PG8_SA(0, 0), a2, voffA);
;             PG8_WAIT_V(8); PG8_WAIT_L(0); PG8_BAR; PG8_MMA(1, 0, At, B0); PG8_MMA(1, 1, At, B1); PG8_BAR; PG8_SCHED;
;             PG8_LDB(B0, 1, 0); PG8_LDB(B1, 1, 1); PG8_SCHED; PG8_LDA(At, 1, 0); PG8_STAGE(PG8_SA(0, 1), a2 + hstep, voffA);
;             PG8_WAIT_V(8); PG8_WAIT_L(0); PG8_BAR; PG8_MMA(0, 0, At, B0); PG8_MMA(0, 1, At, B1); PG8_BAR; PG8_SCHED;
;             PG8_LDA(At, 1, 1); PG8_STAGE(PG8_SB(1, 0), b3, voffB); PG8_STAGE(PG8_SB(1, 1), b3 + hstep, voffB); PG8_STAGE(PG8_SA(1, 0), a3, voffA);
;             PG8_WAIT_V(8); PG8_WAIT_L(0); PG8_BAR; PG8_MMA(1, 0, At, B0); PG8_MMA(1, 1, At, B1); PG8_BAR; PG8_SCHED;
.Lio_skipk2:
	s_setprio 0
	s_barrier
	s_add_i32 s11, s11, s41
	v_lshl_add_u64 v[210:211], v[240:241], 0, s[26:27]
	s_mov_b32 m0, s11
	ds_read_b128 v[198:201], v213 offset:49152
	ds_read_b128 v[202:205], v213 offset:50176
	ds_read_b128 v[206:209], v213 offset:51200
	ds_read_b128 v[220:223], v213 offset:52224
	ds_read_b128 v[224:227], v213 offset:53248
	ds_read_b128 v[228:231], v213 offset:54272
	ds_read_b128 v[232:235], v213 offset:55296
	ds_read_b128 v[236:239], v213 offset:56320
	global_load_lds_dwordx4 v[210:211], off
	v_lshl_add_u64 v[210:211], v[242:243], 0, s[26:27]
	s_add_i32 m0, s11, 0x2000
	s_add_i32 s11, s13, s41
	global_load_lds_dwordx4 v[210:211], off
	v_lshl_add_u64 v[210:211], v[244:245], 0, s[26:27]
	s_mov_b32 m0, s11
	s_nop 0
	global_load_lds_dwordx4 v[210:211], off
	v_lshl_add_u64 v[210:211], v[214:215], 0, s[26:27]
	s_add_i32 m0, s11, 0x2000
	s_nop 0
	global_load_lds_dwordx4 v[210:211], off
	v_lshl_add_u64 v[210:211], v[246:247], 0, s[26:27]
	s_mov_b32 m0, s69
	s_nop 0
	global_load_lds_dwordx4 v[210:211], off
	v_lshl_add_u64 v[210:211], v[248:249], 0, s[26:27]
	s_mov_b32 m0, s70
	s_nop 0
	global_load_lds_dwordx4 v[210:211], off
	s_waitcnt vmcnt(8)
	s_waitcnt lgkmcnt(0)
	s_setprio 1
	s_barrier
	v_mfma_f32_16x16x32_bf16 v[60:63], v[132:135], v[198:201], v[60:63]
	v_mfma_f32_16x16x32_bf16 v[56:59], v[174:177], v[198:201], v[56:59]
	v_mfma_f32_16x16x32_bf16 v[44:47], v[132:135], v[206:209], v[44:47]
	v_mfma_f32_16x16x32_bf16 v[40:43], v[174:177], v[206:209], v[40:43]
	v_mfma_f32_16x16x32_bf16 v[28:31], v[132:135], v[224:227], v[28:31]
	v_mfma_f32_16x16x32_bf16 v[24:27], v[174:177], v[224:227], v[24:27]
	v_mfma_f32_16x16x32_bf16 v[12:15], v[132:135], v[232:235], v[12:15]
	v_mfma_f32_16x16x32_bf16 v[8:11], v[174:177], v[232:235], v[8:11]
	v_mfma_f32_16x16x32_bf16 v[60:63], v[136:139], v[202:205], v[60:63]
	v_mfma_f32_16x16x32_bf16 v[56:59], v[178:181], v[202:205], v[56:59]
	v_mfma_f32_16x16x32_bf16 v[44:47], v[136:139], v[220:223], v[44:47]
	v_mfma_f32_16x16x32_bf16 v[40:43], v[178:181], v[220:223], v[40:43]
	v_mfma_f32_16x16x32_bf16 v[28:31], v[136:139], v[228:231], v[28:31]
	v_mfma_f32_16x16x32_bf16 v[24:27], v[178:181], v[228:231], v[24:27]
	v_mfma_f32_16x16x32_bf16 v[12:15], v[136:139], v[236:239], v[12:15]
	v_mfma_f32_16x16x32_bf16 v[8:11], v[178:181], v[236:239], v[8:11]
	s_cmp_eq_u32 s22, 12
	s_cbranch_scc1 .Lio_skipk3
	v_mfma_f32_16x16x32_bf16 v[52:55], v[182:185], v[198:201], v[52:55]
	v_mfma_f32_16x16x32_bf16 v[48:51], v[190:193], v[198:201], v[48:51]
	v_mfma_f32_16x16x32_bf16 v[36:39], v[182:185], v[206:209], v[36:39]
	v_mfma_f32_16x16x32_bf16 v[32:35], v[190:193], v[206:209], v[32:35]
	v_mfma_f32_16x16x32_bf16 v[20:23], v[182:185], v[224:227], v[20:23]
	v_mfma_f32_16x16x32_bf16 v[16:19], v[190:193], v[224:227], v[16:19]
	v_mfma_f32_16x16x32_bf16 v[4:7], v[182:185], v[232:235], v[4:7]
	v_mfma_f32_16x16x32_bf16 v[0:3], v[190:193], v[232:235], v[0:3]
	v_mfma_f32_16x16x32_bf16 v[52:55], v[186:189], v[202:205], v[52:55]
	v_mfma_f32_16x16x32_bf16 v[48:51], v[194:197], v[202:205], v[48:51]
	v_mfma_f32_16x16x32_bf16 v[36:39], v[186:189], v[220:223], v[36:39]
	v_mfma_f32_16x16x32_bf16 v[32:35], v[194:197], v[220:223], v[32:35]
	v_mfma_f32_16x16x32_bf16 v[20:23], v[186:189], v[228:231], v[20:23]
	v_mfma_f32_16x16x32_bf16 v[16:19], v[194:197], v[228:231], v[16:19]
	v_mfma_f32_16x16x32_bf16 v[4:7], v[186:189], v[236:239], v[4:7]
	v_mfma_f32_16x16x32_bf16 v[0:3], v[194:197], v[236:239], v[0:3]
.Lio_skipk3:
	s_setprio 0
	s_barrier
	v_lshl_add_u64 v[128:129], v[128:129], 0, s[36:37]
	s_cmp_ge_i32 s10, s67
	v_lshl_add_u64 v[130:131], v[130:131], 0, s[36:37]
	s_cbranch_scc0 .LBB0_1423

; template <int MODE>
; __device__ __forceinline__ void attn_unit(const Params& P, int b, int h, int qb, unsigned char* smem) {
;     ...
;   for (int kt = kt_beg; kt < kt_end; ++kt) {
;     const unsigned cur = ((kt - kt_beg) & 1) * BUFSZ, nxt = BUFSZ - cur;
;     const bool more = (kt + 1 < kt_end);
;     if (more) gload(kt + 1);
;     const int k0 = kt * 64;
;     bool active = (k0 <= qw0 + 31);
;     if (MODE == 2) active = active && (k0 + 63 > qw0 - 128);
;     ...
;     if (more) sstore(nxt);
;     __syncthreads();
;   }
.LBB0_1615:
	s_or_b64 exec, exec, s[16:17]
	s_add_i32 s8, s8, 1
	s_add_i32 s21, s21, 64
	v_lshl_add_u64 v[76:77], v[76:77], 0, s[10:11]
	v_lshl_add_u64 v[78:79], v[78:79], 0, s[12:13]
	s_cmp_eq_u32 s20, s8
	v_lshl_add_u64 v[80:81], v[80:81], 0, s[14:15]
	s_waitcnt lgkmcnt(0)
	s_barrier
	s_cbranch_scc1 .LBB0_1626
	.p2align	6
